# hand-scheduled ATT projection epilogue (rms + axial rope, permlane swap row sums, 16-byte stores)
# baseline (speedup 1.0000x reference)
.LBB0_820:
	s_mov_b64 s[8:9], 0
	s_cmp_lt_i32 s21, 4
	s_mov_b64 s[28:29], 0
	s_cbranch_scc1 .LBB0_831
	s_cmp_gt_i32 s21, 4
	s_cbranch_scc0 .LBB0_825
	s_cmp_eq_u32 s21, 5
	s_mov_b64 s[28:29], -1
	s_cbranch_scc0 .LBB0_824
	s_branch .Latt_fast
	s_cmp_gt_i32 s65, 3
	v_readlane_b32 s2, v253, 35
	s_cselect_b64 vcc, -1, 0
	v_ashrrev_i32_e32 v149, 31, v148
	v_mov_b32_e32 v0, s2
	s_and_b64 s[2:3], vcc, exec
	s_movk_i32 s2, 0x78
	s_cselect_b32 s3, 0x80, s2
	s_cselect_b32 s28, 0, s4
	s_cselect_b32 s2, 8, 10
	s_add_i32 s3, s3, 0
	s_add_i32 s3, s3, 0x20000
	ds_read2_b64 v[130:133], v0 offset1:1
	v_mov_b32_e32 v0, s3
	ds_read_b64 v[134:135], v0
	v_cvt_f32_i32_e32 v0, v148
	v_or_b32_e32 v161, 1, v148
	s_waitcnt lgkmcnt(0)
	v_cndmask_b32_e32 v164, v130, v132, vcc
	v_cndmask_b32_e32 v165, v131, v133, vcc
	v_lshl_add_u64 v[130:131], v[148:149], 2, v[134:135]
	global_load_dwordx4 v[142:145], v[130:131], off
	global_load_dwordx4 v[138:141], v[130:131], off offset:64
	global_load_dwordx4 v[134:137], v[130:131], off offset:128
	s_nop 0
	global_load_dwordx4 v[130:133], v[130:131], off offset:192
	v_mul_f32_e32 v149, 0xbf549a78, v0
	s_mov_b32 s3, 0xc2fc0000
	v_cvt_f32_i32_e32 v161, v161
	v_cmp_gt_f32_e64 s[4:5], s3, v149
	v_pk_mul_f32 v[174:175], v[126:127], v[126:127]
	v_and_b32_e32 v173, 63, v163
	v_cndmask_b32_e64 v166, 0, v201, s[4:5]
	v_fmac_f32_e32 v166, 0xbf549a78, v0
	v_exp_f32_e32 v0, v166
	v_mul_f32_e32 v166, 0xbf549a78, v161
	v_cndmask_b32_e64 v149, 0, v200, s[4:5]
	v_cmp_gt_f32_e64 s[4:5], s3, v166
	v_ldexp_f32 v170, v0, v149
	v_or_b32_e32 v149, 3, v148
	v_cndmask_b32_e64 v166, 0, v201, s[4:5]
	v_fmac_f32_e32 v166, 0xbf549a78, v161
	v_exp_f32_e32 v161, v166
	v_or_b32_e32 v166, 2, v148
	v_cvt_f32_i32_e32 v166, v166
	v_cvt_f32_i32_e32 v149, v149
	v_cndmask_b32_e64 v0, 0, v200, s[4:5]
	v_ldexp_f32 v169, v161, v0
	v_mul_f32_e32 v0, 0xbf549a78, v166
	v_mul_f32_e32 v161, 0xbf549a78, v149
	v_cmp_gt_f32_e64 s[4:5], s3, v0
	v_cmp_gt_f32_e64 s[6:7], s3, v161
	s_lshl_b32 s3, s30, 6
	v_cndmask_b32_e64 v0, 0, v201, s[4:5]
	s_add_i32 s3, s3, s28
	v_fmac_f32_e32 v0, 0xbf549a78, v166
	v_add_u32_e32 v166, s3, v148
	v_ashrrev_i32_e32 v167, 31, v166
	v_lshl_add_u64 v[164:165], v[166:167], 1, v[164:165]
	v_pk_mul_f32 v[166:167], v[128:129], v[128:129]
	v_cndmask_b32_e64 v161, 0, v201, s[6:7]
	v_pk_mov_b32 v[208:209], v[174:175], v[166:167] op_sel:[1,0]
	v_mov_b32_e32 v175, v167
	v_pk_add_f32 v[166:167], v[208:209], v[174:175]
	v_exp_f32_e32 v0, v0
	v_fmac_f32_e32 v161, 0xbf549a78, v149
	v_pk_add_f32 v[166:167], v[166:167], v[166:167] op_sel_hi:[0,1]
	v_pk_mul_f32 v[174:175], v[120:121], v[120:121]
	v_pk_mul_f32 v[208:209], v[118:119], v[118:119]
	v_exp_f32_e32 v149, v161
	v_pk_mov_b32 v[210:211], v[208:209], v[174:175] op_sel:[1,0]
	v_mov_b32_e32 v209, v175
	v_mul_f32_e32 v166, v122, v122
	v_pk_add_f32 v[174:175], v[210:211], v[208:209]
	v_pk_fma_f32 v[208:209], v[122:123], v[122:123], v[166:167] op_sel_hi:[1,1,0]
	v_mul_f32_e32 v166, v124, v124
	v_cndmask_b32_e64 v161, 0, v200, s[4:5]
	v_pk_add_f32 v[174:175], v[174:175], v[174:175] op_sel_hi:[0,1]
	v_pk_fma_f32 v[210:211], v[124:125], v[124:125], v[166:167] op_sel_hi:[1,1,0]
	v_ldexp_f32 v168, v0, v161
	v_cndmask_b32_e64 v0, 0, v200, s[6:7]
	v_mul_f32_e32 v208, v114, v114
	v_mul_f32_e32 v210, v115, v115
	v_mul_f32_e32 v174, v116, v116
	v_mul_f32_e32 v166, v117, v117
	v_ldexp_f32 v149, v149, v0
	v_mov_b32_e32 v0, 0x3e000000
	v_pk_add_f32 v[208:209], v[208:209], v[210:211]
	v_pk_add_f32 v[166:167], v[174:175], v[166:167]
	v_cndmask_b32_e64 v0, v0, 1.0, vcc
	v_cmp_lt_i32_e32 vcc, v195, v190
	v_pk_add_f32 v[166:167], v[208:209], v[166:167]
	v_pk_mul_f32 v[208:209], v[112:113], v[112:113]
	v_pk_mul_f32 v[210:211], v[110:111], v[110:111]
	v_cndmask_b32_e32 v161, v179, v195, vcc
	v_cmp_lt_i32_e32 vcc, v196, v190
	v_pk_mov_b32 v[212:213], v[210:211], v[208:209] op_sel:[1,0]
	v_mov_b32_e32 v211, v209
	v_lshlrev_b32_e32 v172, 2, v161
	v_cndmask_b32_e32 v161, v179, v196, vcc
	v_pk_add_f32 v[208:209], v[212:213], v[210:211]
	v_lshlrev_b32_e32 v171, 2, v161
	v_add_u32_e32 v161, 16, v163
	v_pk_add_f32 v[208:209], v[208:209], v[208:209] op_sel_hi:[0,1]
	v_pk_mul_f32 v[210:211], v[104:105], v[104:105]
	v_pk_mul_f32 v[212:213], v[102:103], v[102:103]
	v_and_b32_e32 v177, 63, v161
	v_add_u32_e32 v161, 48, v163
	v_pk_mov_b32 v[230:231], v[212:213], v[210:211] op_sel:[1,0]
	v_mov_b32_e32 v213, v211
	v_mul_f32_e32 v208, v106, v106
	v_and_b32_e32 v225, 63, v161
	v_ashrrev_i32_e32 v161, 6, v160
	v_pk_add_f32 v[210:211], v[230:231], v[212:213]
	v_pk_fma_f32 v[212:213], v[106:107], v[106:107], v[208:209] op_sel_hi:[1,1,0]
	v_mul_f32_e32 v208, v108, v108
	v_cvt_f32_i32_e32 v180, v161
	v_pk_add_f32 v[210:211], v[210:211], v[210:211] op_sel_hi:[0,1]
	v_pk_fma_f32 v[230:231], v[108:109], v[108:109], v[208:209] op_sel_hi:[1,1,0]
	v_mul_f32_e32 v212, v98, v98
	v_mul_f32_e32 v230, v99, v99
	v_mul_f32_e32 v210, v100, v100
	v_mul_f32_e32 v208, v101, v101
	v_pk_add_f32 v[212:213], v[212:213], v[230:231]
	v_pk_add_f32 v[208:209], v[210:211], v[208:209]
	v_ashrrev_i32_e32 v161, 31, v160
	v_pk_add_f32 v[208:209], v[212:213], v[208:209]
	v_lshlrev_b64 v[174:175], s2, v[160:161]
	v_mul_f32_e32 v161, v170, v180
	v_mov_b32_e32 v210, v208
	v_mov_b32_e32 v211, v166
	v_mov_b32_e32 v166, v209
	v_mul_f32_e32 v161, 0.15915494, v161
	v_pk_add_f32 v[166:167], v[210:211], v[166:167]
	v_lshl_add_u64 v[214:215], v[174:175], 1, v[164:165]
	v_cos_f32_e32 v174, v161
	v_sin_f32_e32 v161, v161
	ds_bpermute_b32 v209, v172, v167
	ds_bpermute_b32 v208, v172, v166
	v_cmp_gt_i32_e32 vcc, s86, v160
	v_mul_f32_e32 v175, v169, v180
	v_mul_f32_e32 v175, 0.15915494, v175
	v_cndmask_b32_e32 v218, 0, v161, vcc
	v_mul_f32_e32 v161, v168, v180
	v_mul_f32_e32 v161, 0.15915494, v161
	s_waitcnt lgkmcnt(0)
	v_pk_add_f32 v[166:167], v[166:167], v[208:209]
	v_cndmask_b32_e32 v216, 1.0, v174, vcc
	v_mul_f32_e32 v174, v149, v180
	v_cos_f32_e32 v180, v161
	ds_bpermute_b32 v231, v171, v167
	ds_bpermute_b32 v230, v171, v166
	v_cos_f32_e32 v181, v175
	v_sin_f32_e32 v161, v161
	v_cndmask_b32_e32 v220, 1.0, v180, vcc
	v_cvt_f32_ubyte0_e32 v180, v173
	s_mov_b32 s4, 0x358637bd
	v_cndmask_b32_e32 v217, 1.0, v181, vcc
	v_cndmask_b32_e32 v222, 0, v161, vcc
	v_mul_f32_e32 v161, v170, v180
	v_mul_f32_e32 v173, v169, v180
	v_mul_f32_e32 v181, v168, v180
	v_mul_f32_e32 v180, v149, v180
	s_waitcnt lgkmcnt(0)
	v_pk_add_f32 v[230:231], v[166:167], v[230:231]
	v_mov_b64_e32 v[166:167], s[4:5]
	s_mov_b32 s6, 0x3c800000
	v_mul_f32_e32 v180, 0.15915494, v180
	v_pk_fma_f32 v[230:231], v[230:231], s[6:7], v[166:167] op_sel_hi:[1,0,0]
	s_mov_b32 s3, 0x800000
	v_cos_f32_e32 v212, v180
	v_sin_f32_e32 v211, v180
	v_mul_f32_e32 v180, 0x4b800000, v231
	v_cmp_gt_f32_e64 s[4:5], s3, v231
	v_sin_f32_e32 v175, v175
	v_mul_f32_e32 v181, 0.15915494, v181
	v_cndmask_b32_e64 v180, v231, v180, s[4:5]
	v_rsq_f32_e32 v180, v180
	v_sin_f32_e32 v209, v181
	v_mul_f32_e32 v174, 0.15915494, v174
	v_cos_f32_e32 v210, v181
	v_mul_f32_e32 v181, 0x45800000, v180
	v_cndmask_b32_e32 v219, 0, v175, vcc
	v_cos_f32_e32 v175, v174
	v_sin_f32_e32 v174, v174
	v_cndmask_b32_e64 v208, v180, v181, s[4:5]
	v_pk_mul_f32 v[242:243], v[126:127], v[208:209] op_sel_hi:[1,0]
	v_pk_mul_f32 v[244:245], v[122:123], v[208:209] op_sel_hi:[1,0]
	s_waitcnt vmcnt(0)
	v_pk_mul_f32 v[242:243], v[142:143], v[242:243]
	v_pk_mul_f32 v[244:245], v[138:139], v[244:245]
	v_mul_f32_e32 v161, 0.15915494, v161
	v_mul_f32_e32 v173, 0.15915494, v173
	v_pk_mul_f32 v[246:247], v[218:219], v[242:243]
	v_pk_mul_f32 v[218:219], v[218:219], v[244:245]
	v_cndmask_b32_e32 v221, 1.0, v175, vcc
	v_cndmask_b32_e32 v223, 0, v174, vcc
	v_cos_f32_e32 v174, v161
	v_cos_f32_e32 v175, v173
	v_sin_f32_e32 v161, v161
	v_sin_f32_e32 v173, v173
	v_pk_fma_f32 v[246:247], v[216:217], v[244:245], v[246:247]
	v_pk_fma_f32 v[216:217], v[216:217], v[242:243], v[218:219] neg_lo:[0,0,1] neg_hi:[0,0,1]
	v_pk_mul_f32 v[218:219], v[128:129], v[208:209] op_sel_hi:[1,0]
	v_pk_mul_f32 v[242:243], v[124:125], v[208:209] op_sel_hi:[1,0]
	v_pk_mul_f32 v[218:219], v[144:145], v[218:219]
	v_pk_mul_f32 v[242:243], v[140:141], v[242:243]
	v_pk_mul_f32 v[244:245], v[222:223], v[218:219]
	v_pk_mul_f32 v[222:223], v[222:223], v[242:243]
	v_cndmask_b32_e32 v226, 1.0, v174, vcc
	v_pk_fma_f32 v[218:219], v[220:221], v[218:219], v[222:223] neg_lo:[0,0,1] neg_hi:[0,0,1]
	v_cndmask_b32_e32 v227, 1.0, v175, vcc
	v_cndmask_b32_e32 v228, 0, v161, vcc
	v_cndmask_b32_e32 v229, 0, v173, vcc
	v_cndmask_b32_e32 v237, 1.0, v212, vcc
	v_cndmask_b32_e32 v236, 1.0, v210, vcc
	v_cndmask_b32_e32 v239, 0, v211, vcc
	v_cndmask_b32_e32 v238, 0, v209, vcc
	v_pk_mul_f32 v[216:217], v[0:1], v[216:217] op_sel_hi:[0,1]
	v_pk_fma_f32 v[244:245], v[220:221], v[242:243], v[244:245]
	v_pk_mul_f32 v[218:219], v[0:1], v[218:219] op_sel_hi:[0,1]
	v_mul_f32_e32 v180, 0x4b800000, v230
	v_cmp_gt_f32_e32 vcc, s3, v230
	v_pk_mul_f32 v[246:247], v[0:1], v[246:247] op_sel_hi:[0,1]
	v_pk_mul_f32 v[244:245], v[0:1], v[244:245] op_sel_hi:[0,1]
	v_cvt_pk_bf16_f32 v216, v216, v217
	v_cvt_pk_bf16_f32 v217, v218, v219
	v_cndmask_b32_e32 v180, v230, v180, vcc
	global_store_dwordx2 v[214:215], v[216:217], off
	v_cvt_pk_bf16_f32 v216, v246, v247
	v_cvt_pk_bf16_f32 v217, v244, v245
	v_rsq_f32_e32 v180, v180
	global_store_dwordx2 v[214:215], v[216:217], off offset:64
	v_pk_mul_f32 v[216:217], v[118:119], v[208:209] op_sel_hi:[1,0]
	v_pk_mul_f32 v[218:219], v[114:115], v[208:209] op_sel_hi:[1,0]
	v_pk_mul_f32 v[216:217], v[134:135], v[216:217]
	v_pk_mul_f32 v[218:219], v[130:131], v[218:219]
	v_pk_mul_f32 v[220:221], v[228:229], v[216:217]
	v_add_u32_e32 v240, 16, v160
	v_pk_fma_f32 v[220:221], v[226:227], v[218:219], v[220:221]
	v_pk_mul_f32 v[218:219], v[228:229], v[218:219]
	v_mul_f32_e32 v181, 0x45800000, v180
	v_pk_fma_f32 v[216:217], v[226:227], v[216:217], v[218:219] neg_lo:[0,0,1] neg_hi:[0,0,1]
	v_pk_mul_f32 v[218:219], v[120:121], v[208:209] op_sel_hi:[1,0]
	v_pk_mul_f32 v[222:223], v[116:117], v[208:209] op_sel_hi:[1,0]
	v_cndmask_b32_e32 v208, v180, v181, vcc
	v_ashrrev_i32_e32 v180, 6, v240
	v_cvt_f32_i32_e32 v180, v180
	v_pk_mul_f32 v[218:219], v[136:137], v[218:219]
	v_pk_mul_f32 v[222:223], v[132:133], v[222:223]
	v_pk_mul_f32 v[226:227], v[238:239], v[218:219]
	v_mul_f32_e32 v181, v170, v180
	v_mul_f32_e32 v181, 0.15915494, v181
	v_pk_fma_f32 v[226:227], v[236:237], v[222:223], v[226:227]
	v_pk_mul_f32 v[222:223], v[238:239], v[222:223]
	v_cos_f32_e32 v182, v181
	v_sin_f32_e32 v181, v181
	v_mul_f32_e32 v183, v169, v180
	v_pk_fma_f32 v[218:219], v[236:237], v[218:219], v[222:223] neg_lo:[0,0,1] neg_hi:[0,0,1]
	v_mul_f32_e32 v183, 0.15915494, v183
	v_pk_mul_f32 v[216:217], v[0:1], v[216:217] op_sel_hi:[0,1]
	v_pk_mul_f32 v[218:219], v[0:1], v[218:219] op_sel_hi:[0,1]
	v_cos_f32_e32 v184, v183
	v_sin_f32_e32 v183, v183
	s_movk_i32 s4, 0x3ff0
	v_pk_mul_f32 v[220:221], v[0:1], v[220:221] op_sel_hi:[0,1]
	v_pk_mul_f32 v[226:227], v[0:1], v[226:227] op_sel_hi:[0,1]
	v_cvt_pk_bf16_f32 v216, v216, v217
	v_cvt_pk_bf16_f32 v217, v218, v219
	v_cmp_gt_i32_e32 vcc, s4, v160
	global_store_dwordx2 v[214:215], v[216:217], off offset:32
	v_cvt_pk_bf16_f32 v216, v220, v221
	v_cvt_pk_bf16_f32 v217, v226, v227
	v_ashrrev_i32_e32 v241, 31, v240
	v_cndmask_b32_e32 v218, 0, v181, vcc
	v_mul_f32_e32 v181, v168, v180
	v_mul_f32_e32 v180, v149, v180
	global_store_dwordx2 v[214:215], v[216:217], off offset:96
	v_lshlrev_b64 v[214:215], s2, v[240:241]
	v_mul_f32_e32 v181, 0.15915494, v181
	v_mul_f32_e32 v180, 0.15915494, v180
	v_lshl_add_u64 v[222:223], v[214:215], 1, v[164:165]
	v_cndmask_b32_e32 v214, 1.0, v182, vcc
	v_pk_mul_f32 v[216:217], v[110:111], v[208:209] op_sel_hi:[1,0]
	v_cndmask_b32_e32 v219, 0, v183, vcc
	v_pk_mul_f32 v[220:221], v[106:107], v[208:209] op_sel_hi:[1,0]
	v_cos_f32_e32 v182, v180
	v_cos_f32_e32 v183, v181
	v_sin_f32_e32 v181, v181
	v_sin_f32_e32 v180, v180
	v_pk_mul_f32 v[216:217], v[142:143], v[216:217]
	v_pk_mul_f32 v[220:221], v[138:139], v[220:221]
	v_cndmask_b32_e32 v215, 1.0, v184, vcc
	v_pk_mul_f32 v[226:227], v[218:219], v[216:217]
	v_pk_mul_f32 v[218:219], v[218:219], v[220:221]
	v_pk_fma_f32 v[226:227], v[214:215], v[220:221], v[226:227]
	v_pk_fma_f32 v[214:215], v[214:215], v[216:217], v[218:219] neg_lo:[0,0,1] neg_hi:[0,0,1]
	v_pk_mul_f32 v[218:219], v[112:113], v[208:209] op_sel_hi:[1,0]
	v_pk_mul_f32 v[228:229], v[108:109], v[208:209] op_sel_hi:[1,0]
	v_pk_mul_f32 v[218:219], v[144:145], v[218:219]
	v_cndmask_b32_e32 v221, 0, v180, vcc
	v_cndmask_b32_e32 v220, 0, v181, vcc
	v_pk_mul_f32 v[228:229], v[140:141], v[228:229]
	v_cndmask_b32_e32 v217, 1.0, v182, vcc
	v_cndmask_b32_e32 v216, 1.0, v183, vcc
	v_pk_mul_f32 v[230:231], v[220:221], v[218:219]
	v_pk_mul_f32 v[220:221], v[220:221], v[228:229]
	v_pk_fma_f32 v[230:231], v[216:217], v[228:229], v[230:231]
	v_pk_fma_f32 v[216:217], v[216:217], v[218:219], v[220:221] neg_lo:[0,0,1] neg_hi:[0,0,1]
	v_pk_mul_f32 v[214:215], v[0:1], v[214:215] op_sel_hi:[0,1]
	v_pk_mul_f32 v[216:217], v[0:1], v[216:217] op_sel_hi:[0,1]
	v_cvt_f32_ubyte0_e32 v177, v177
	v_pk_mul_f32 v[226:227], v[0:1], v[226:227] op_sel_hi:[0,1]
	v_pk_mul_f32 v[230:231], v[0:1], v[230:231] op_sel_hi:[0,1]
	v_cvt_pk_bf16_f32 v214, v214, v215
	v_cvt_pk_bf16_f32 v215, v216, v217
	v_mul_f32_e32 v180, v170, v177
	v_mul_f32_e32 v181, v169, v177
	global_store_dwordx2 v[222:223], v[214:215], off
	v_cvt_pk_bf16_f32 v214, v226, v227
	v_cvt_pk_bf16_f32 v215, v230, v231
	v_mul_f32_e32 v180, 0.15915494, v180
	v_mul_f32_e32 v181, 0.15915494, v181
	global_store_dwordx2 v[222:223], v[214:215], off offset:64
	v_sin_f32_e32 v213, v180
	v_sin_f32_e32 v214, v181
	v_cos_f32_e32 v215, v180
	v_cos_f32_e32 v216, v181
	v_pk_mul_f32 v[220:221], v[102:103], v[208:209] op_sel_hi:[1,0]
	v_pk_mul_f32 v[228:229], v[98:99], v[208:209] op_sel_hi:[1,0]
	v_pk_mul_f32 v[220:221], v[134:135], v[220:221]
	v_cndmask_b32_e32 v226, 0, v213, vcc
	v_cndmask_b32_e32 v227, 0, v214, vcc
	v_pk_mul_f32 v[228:229], v[130:131], v[228:229]
	v_cndmask_b32_e32 v218, 1.0, v215, vcc
	v_cndmask_b32_e32 v219, 1.0, v216, vcc
	v_pk_mul_f32 v[230:231], v[226:227], v[220:221]
	v_pk_mul_f32 v[226:227], v[226:227], v[228:229]
	v_mul_f32_e32 v180, v168, v177
	v_mul_f32_e32 v177, v149, v177
	v_pk_fma_f32 v[230:231], v[218:219], v[228:229], v[230:231]
	v_pk_fma_f32 v[218:219], v[218:219], v[220:221], v[226:227] neg_lo:[0,0,1] neg_hi:[0,0,1]
	v_mul_f32_e32 v180, 0.15915494, v180
	v_mul_f32_e32 v177, 0.15915494, v177
	v_pk_mul_f32 v[226:227], v[0:1], v[218:219] op_sel_hi:[0,1]
	v_sin_f32_e32 v217, v180
	v_sin_f32_e32 v218, v177
	v_cos_f32_e32 v220, v177
	v_cos_f32_e32 v219, v180
	v_pk_mul_f32 v[236:237], v[104:105], v[208:209] op_sel_hi:[1,0]
	v_pk_mul_f32 v[240:241], v[100:101], v[208:209] op_sel_hi:[1,0]
	v_pk_mul_f32 v[236:237], v[136:137], v[236:237]
	v_cndmask_b32_e32 v239, 0, v218, vcc
	v_cndmask_b32_e32 v238, 0, v217, vcc
	v_pk_mul_f32 v[240:241], v[132:133], v[240:241]
	v_cndmask_b32_e32 v229, 1.0, v220, vcc
	v_cndmask_b32_e32 v228, 1.0, v219, vcc
	v_pk_mul_f32 v[242:243], v[238:239], v[236:237]
	v_pk_mul_f32 v[238:239], v[238:239], v[240:241]
	v_pk_fma_f32 v[242:243], v[228:229], v[240:241], v[242:243]
	v_pk_fma_f32 v[228:229], v[228:229], v[236:237], v[238:239] neg_lo:[0,0,1] neg_hi:[0,0,1]
	v_pk_mul_f32 v[230:231], v[0:1], v[230:231] op_sel_hi:[0,1]
	v_pk_mul_f32 v[228:229], v[0:1], v[228:229] op_sel_hi:[0,1]
	v_pk_mul_f32 v[242:243], v[0:1], v[242:243] op_sel_hi:[0,1]
	v_cvt_pk_bf16_f32 v226, v226, v227
	v_cvt_pk_bf16_f32 v227, v228, v229
	global_store_dwordx2 v[222:223], v[226:227], off offset:32
	v_cvt_pk_bf16_f32 v226, v230, v231
	v_cvt_pk_bf16_f32 v227, v242, v243
	global_store_dwordx2 v[222:223], v[226:227], off offset:96
	v_pk_mul_f32 v[226:227], v[96:97], v[96:97]
	v_pk_mul_f32 v[228:229], v[94:95], v[94:95]
	v_add_u32_e32 v222, 32, v160
	v_pk_mov_b32 v[230:231], v[228:229], v[226:227] op_sel:[1,0]
	v_mov_b32_e32 v229, v227
	v_pk_add_f32 v[226:227], v[230:231], v[228:229]
	v_pk_mul_f32 v[228:229], v[88:89], v[88:89]
	v_pk_mul_f32 v[230:231], v[86:87], v[86:87]
	v_pk_add_f32 v[226:227], v[226:227], v[226:227] op_sel_hi:[0,1]
	v_pk_mov_b32 v[236:237], v[230:231], v[228:229] op_sel:[1,0]
	v_mov_b32_e32 v231, v229
	v_pk_add_f32 v[228:229], v[236:237], v[230:231]
	v_ashrrev_i32_e32 v223, 31, v222
	v_pk_add_f32 v[228:229], v[228:229], v[228:229] op_sel_hi:[0,1]
	v_mul_f32_e32 v228, v84, v84
	v_mul_f32_e32 v226, v85, v85
	v_ashrrev_i32_e32 v177, 6, v222
	v_lshlrev_b64 v[222:223], s2, v[222:223]
	v_pk_add_f32 v[226:227], v[228:229], v[226:227]
	v_lshl_add_u64 v[228:229], v[222:223], 1, v[164:165]
	v_pk_mul_f32 v[222:223], v[80:81], v[80:81]
	v_pk_mul_f32 v[246:247], v[78:79], v[78:79]
	v_mul_f32_e32 v208, v90, v90
	v_pk_mov_b32 v[248:249], v[246:247], v[222:223] op_sel:[1,0]
	v_mov_b32_e32 v247, v223
	v_pk_add_f32 v[222:223], v[248:249], v[246:247]
	v_pk_mul_f32 v[246:247], v[72:73], v[72:73]
	v_pk_add_f32 v[222:223], v[222:223], v[222:223] op_sel_hi:[0,1]
	v_pk_mul_f32 v[248:249], v[70:71], v[70:71]
	v_mul_f32_e32 v222, v74, v74
	v_pk_mov_b32 v[250:251], v[248:249], v[246:247] op_sel:[1,0]
	v_mov_b32_e32 v249, v247
	v_pk_fma_f32 v[230:231], v[90:91], v[90:91], v[208:209] op_sel_hi:[1,1,0]
	v_mul_f32_e32 v208, v92, v92
	v_pk_add_f32 v[246:247], v[250:251], v[248:249]
	v_pk_fma_f32 v[248:249], v[74:75], v[74:75], v[222:223] op_sel_hi:[1,1,0]
	v_mul_f32_e32 v222, v76, v76
	v_pk_fma_f32 v[236:237], v[92:93], v[92:93], v[208:209] op_sel_hi:[1,1,0]
	v_cvt_f32_i32_e32 v177, v177
	v_pk_add_f32 v[246:247], v[246:247], v[246:247] op_sel_hi:[0,1]
	v_pk_fma_f32 v[250:251], v[76:77], v[76:77], v[222:223] op_sel_hi:[1,1,0]
	v_mul_f32_e32 v230, v82, v82
	v_mul_f32_e32 v236, v83, v83
	v_mul_f32_e32 v248, v66, v66
	v_mul_f32_e32 v250, v67, v67
	v_mul_f32_e32 v246, v68, v68
	v_mul_f32_e32 v222, v69, v69
	v_pk_add_f32 v[230:231], v[230:231], v[236:237]
	v_pk_add_f32 v[248:249], v[248:249], v[250:251]
	v_pk_add_f32 v[222:223], v[246:247], v[222:223]
	v_pk_add_f32 v[226:227], v[230:231], v[226:227]
	v_pk_add_f32 v[222:223], v[248:249], v[222:223]
	v_mul_f32_e32 v180, v170, v177
	v_mov_b32_e32 v246, v222
	v_mov_b32_e32 v247, v226
	v_mov_b32_e32 v226, v223
	v_mul_f32_e32 v180, 0.15915494, v180
	v_pk_add_f32 v[226:227], v[246:247], v[226:227]
	v_cos_f32_e32 v181, v180
	v_sin_f32_e32 v180, v180
	v_mul_f32_e32 v182, v169, v177
	ds_bpermute_b32 v247, v172, v227
	ds_bpermute_b32 v246, v172, v226
	v_mul_f32_e32 v182, 0.15915494, v182
	v_cos_f32_e32 v183, v182
	v_sin_f32_e32 v182, v182
	s_movk_i32 s4, 0x3fe0
	v_cmp_gt_i32_e32 vcc, s4, v160
	s_waitcnt lgkmcnt(0)
	v_pk_add_f32 v[226:227], v[226:227], v[246:247]
	ds_bpermute_b32 v247, v171, v227
	v_cndmask_b32_e32 v236, 0, v180, vcc
	v_mul_f32_e32 v180, v168, v177
	v_mul_f32_e32 v180, 0.15915494, v180
	v_mul_f32_e32 v177, v149, v177
	v_cndmask_b32_e32 v237, 0, v182, vcc
	v_mul_f32_e32 v177, 0.15915494, v177
	v_cos_f32_e32 v182, v180
	v_sin_f32_e32 v180, v180
	ds_bpermute_b32 v246, v171, v226
	v_cndmask_b32_e32 v230, 1.0, v181, vcc
	v_cos_f32_e32 v181, v177
	v_sin_f32_e32 v177, v177
	v_bitop3_b32 v176, v163, 32, 63 bitop3:0x6c
	v_cndmask_b32_e32 v240, 0, v180, vcc
	v_cvt_f32_ubyte0_e32 v180, v176
	v_cndmask_b32_e32 v239, 1.0, v181, vcc
	v_cndmask_b32_e32 v241, 0, v177, vcc
	v_mul_f32_e32 v176, v170, v180
	v_mul_f32_e32 v177, v169, v180
	v_mul_f32_e32 v181, v168, v180
	v_mul_f32_e32 v180, v149, v180
	s_waitcnt lgkmcnt(0)
	v_pk_add_f32 v[226:227], v[226:227], v[246:247]
	v_mul_f32_e32 v180, 0.15915494, v180
	v_pk_fma_f32 v[226:227], v[226:227], s[6:7], v[166:167] op_sel_hi:[1,0,0]
	v_cos_f32_e32 v224, v180
	v_sin_f32_e32 v222, v180
	v_mul_f32_e32 v180, 0x4b800000, v227
	v_cmp_gt_f32_e64 s[4:5], s3, v227
	v_mul_f32_e32 v181, 0.15915494, v181
	v_cos_f32_e32 v223, v181
	v_cndmask_b32_e64 v180, v227, v180, s[4:5]
	v_rsq_f32_e32 v180, v180
	v_sin_f32_e32 v221, v181
	v_cndmask_b32_e32 v231, 1.0, v183, vcc
	v_cndmask_b32_e32 v238, 1.0, v182, vcc
	v_mul_f32_e32 v181, 0x45800000, v180
	v_cndmask_b32_e64 v232, v180, v181, s[4:5]
	v_pk_mul_f32 v[184:185], v[94:95], v[232:233] op_sel_hi:[1,0]
	v_pk_mul_f32 v[234:235], v[90:91], v[232:233] op_sel_hi:[1,0]
	v_pk_mul_f32 v[184:185], v[142:143], v[184:185]
	v_pk_mul_f32 v[234:235], v[138:139], v[234:235]
	v_pk_mul_f32 v[180:181], v[236:237], v[184:185]
	v_mul_f32_e32 v176, 0.15915494, v176
	v_pk_fma_f32 v[180:181], v[230:231], v[234:235], v[180:181]
	v_pk_mul_f32 v[234:235], v[236:237], v[234:235]
	v_mul_f32_e32 v177, 0.15915494, v177
	v_pk_fma_f32 v[184:185], v[230:231], v[184:185], v[234:235] neg_lo:[0,0,1] neg_hi:[0,0,1]
	v_pk_mul_f32 v[230:231], v[96:97], v[232:233] op_sel_hi:[1,0]
	v_pk_mul_f32 v[234:235], v[92:93], v[232:233] op_sel_hi:[1,0]
	v_pk_mul_f32 v[230:231], v[144:145], v[230:231]
	v_pk_mul_f32 v[234:235], v[140:141], v[234:235]
	v_pk_mul_f32 v[236:237], v[240:241], v[230:231]
	v_cos_f32_e32 v207, v176
	v_cos_f32_e32 v208, v177
	v_sin_f32_e32 v176, v176
	v_sin_f32_e32 v177, v177
	v_pk_fma_f32 v[236:237], v[238:239], v[234:235], v[236:237]
	v_pk_mul_f32 v[234:235], v[240:241], v[234:235]
	v_pk_mul_f32 v[180:181], v[0:1], v[180:181] op_sel_hi:[0,1]
	v_pk_mul_f32 v[236:237], v[0:1], v[236:237] op_sel_hi:[0,1]
	v_pk_fma_f32 v[230:231], v[238:239], v[230:231], v[234:235] neg_lo:[0,0,1] neg_hi:[0,0,1]
	v_pk_mul_f32 v[184:185], v[0:1], v[184:185] op_sel_hi:[0,1]
	v_pk_mul_f32 v[230:231], v[0:1], v[230:231] op_sel_hi:[0,1]
	v_cvt_pk_bf16_f32 v180, v180, v181
	v_cvt_pk_bf16_f32 v181, v236, v237
	v_cvt_pk_bf16_f32 v184, v184, v185
	v_cvt_pk_bf16_f32 v185, v230, v231
	global_store_dwordx2 v[228:229], v[180:181], off offset:64
	v_pk_mul_f32 v[180:181], v[86:87], v[232:233] op_sel_hi:[1,0]
	v_cndmask_b32_e32 v244, 0, v176, vcc
	v_cndmask_b32_e32 v245, 0, v177, vcc
	global_store_dwordx2 v[228:229], v[184:185], off
	v_pk_mul_f32 v[180:181], v[134:135], v[180:181]
	v_pk_mul_f32 v[184:185], v[82:83], v[232:233] op_sel_hi:[1,0]
	v_cndmask_b32_e32 v242, 1.0, v207, vcc
	v_cndmask_b32_e32 v243, 1.0, v208, vcc
	v_pk_mul_f32 v[184:185], v[130:131], v[184:185]
	v_pk_mul_f32 v[230:231], v[244:245], v[180:181]
	v_cndmask_b32_e32 v247, 0, v222, vcc
	v_pk_fma_f32 v[230:231], v[242:243], v[184:185], v[230:231]
	v_pk_mul_f32 v[184:185], v[244:245], v[184:185]
	v_cndmask_b32_e32 v246, 0, v221, vcc
	v_pk_fma_f32 v[180:181], v[242:243], v[180:181], v[184:185] neg_lo:[0,0,1] neg_hi:[0,0,1]
	v_pk_mul_f32 v[184:185], v[88:89], v[232:233] op_sel_hi:[1,0]
	v_pk_mul_f32 v[234:235], v[84:85], v[232:233] op_sel_hi:[1,0]
	v_pk_mul_f32 v[184:185], v[136:137], v[184:185]
	v_cndmask_b32_e32 v249, 1.0, v224, vcc
	v_cndmask_b32_e32 v248, 1.0, v223, vcc
	v_pk_mul_f32 v[234:235], v[132:133], v[234:235]
	v_pk_mul_f32 v[236:237], v[246:247], v[184:185]
	v_pk_mul_f32 v[180:181], v[0:1], v[180:181] op_sel_hi:[0,1]
	v_pk_fma_f32 v[236:237], v[248:249], v[234:235], v[236:237]
	v_pk_mul_f32 v[234:235], v[246:247], v[234:235]
	v_cvt_pk_bf16_f32 v180, v180, v181
	v_pk_fma_f32 v[184:185], v[248:249], v[184:185], v[234:235] neg_lo:[0,0,1] neg_hi:[0,0,1]
	v_cmp_gt_f32_e32 vcc, s3, v226
	v_pk_mul_f32 v[184:185], v[0:1], v[184:185] op_sel_hi:[0,1]
	v_cvt_pk_bf16_f32 v181, v184, v185
	global_store_dwordx2 v[228:229], v[180:181], off offset:32
	v_mul_f32_e32 v180, 0x4b800000, v226
	v_pk_mul_f32 v[230:231], v[0:1], v[230:231] op_sel_hi:[0,1]
	v_pk_mul_f32 v[236:237], v[0:1], v[236:237] op_sel_hi:[0,1]
	v_cndmask_b32_e32 v180, v226, v180, vcc
	v_add_u32_e32 v250, 48, v160
	v_rsq_f32_e32 v182, v180
	v_cvt_pk_bf16_f32 v180, v230, v231
	v_cvt_pk_bf16_f32 v181, v236, v237
	global_store_dwordx2 v[228:229], v[180:181], off offset:96
	v_ashrrev_i32_e32 v181, 6, v250
	v_cvt_f32_i32_e32 v181, v181
	v_mul_f32_e32 v180, 0x45800000, v182
	v_cndmask_b32_e32 v180, v182, v180, vcc
	s_movk_i32 s4, 0x3fd0
	v_mul_f32_e32 v182, v170, v181
	v_mul_f32_e32 v182, 0.15915494, v182
	v_mul_f32_e32 v226, v169, v181
	v_cos_f32_e32 v183, v182
	v_sin_f32_e32 v182, v182
	v_mul_f32_e32 v226, 0.15915494, v226
	v_sin_f32_e32 v231, v226
	v_cos_f32_e32 v227, v226
	v_cmp_gt_i32_e32 vcc, s4, v160
	v_pk_mul_f32 v[228:229], v[78:79], v[180:181] op_sel_hi:[1,0]
	v_pk_mul_f32 v[234:235], v[74:75], v[180:181] op_sel_hi:[1,0]
	v_cndmask_b32_e32 v230, 0, v182, vcc
	v_mul_f32_e32 v182, v168, v181
	v_mul_f32_e32 v181, v149, v181
	v_pk_mul_f32 v[228:229], v[142:143], v[228:229]
	v_cndmask_b32_e32 v231, 0, v231, vcc
	v_pk_mul_f32 v[234:235], v[138:139], v[234:235]
	v_mul_f32_e32 v181, 0.15915494, v181
	v_cndmask_b32_e32 v226, 1.0, v183, vcc
	v_cndmask_b32_e32 v227, 1.0, v227, vcc
	v_pk_mul_f32 v[236:237], v[230:231], v[228:229]
	v_pk_mul_f32 v[230:231], v[230:231], v[234:235]
	v_mul_f32_e32 v182, 0.15915494, v182
	v_cos_f32_e32 v183, v181
	v_sin_f32_e32 v181, v181
	v_pk_fma_f32 v[236:237], v[226:227], v[234:235], v[236:237]
	v_pk_fma_f32 v[226:227], v[226:227], v[228:229], v[230:231] neg_lo:[0,0,1] neg_hi:[0,0,1]
	v_cos_f32_e32 v228, v182
	v_sin_f32_e32 v182, v182
	v_pk_mul_f32 v[230:231], v[80:81], v[180:181] op_sel_hi:[1,0]
	v_pk_mul_f32 v[238:239], v[76:77], v[180:181] op_sel_hi:[1,0]
	v_pk_mul_f32 v[230:231], v[144:145], v[230:231]
	v_cndmask_b32_e32 v235, 0, v181, vcc
	v_cndmask_b32_e32 v234, 0, v182, vcc
	v_pk_mul_f32 v[238:239], v[140:141], v[238:239]
	v_cndmask_b32_e32 v229, 1.0, v183, vcc
	v_cndmask_b32_e32 v228, 1.0, v228, vcc
	v_pk_mul_f32 v[240:241], v[234:235], v[230:231]
	v_pk_mul_f32 v[234:235], v[234:235], v[238:239]
	v_ashrrev_i32_e32 v251, 31, v250
	v_pk_fma_f32 v[240:241], v[228:229], v[238:239], v[240:241]
	v_pk_fma_f32 v[228:229], v[228:229], v[230:231], v[234:235] neg_lo:[0,0,1] neg_hi:[0,0,1]
	v_lshlrev_b64 v[184:185], s2, v[250:251]
	v_pk_mul_f32 v[226:227], v[0:1], v[226:227] op_sel_hi:[0,1]
	v_pk_mul_f32 v[228:229], v[0:1], v[228:229] op_sel_hi:[0,1]
	v_cvt_f32_ubyte0_e32 v181, v225
	v_lshl_add_u64 v[184:185], v[184:185], 1, v[164:165]
	v_pk_mul_f32 v[236:237], v[0:1], v[236:237] op_sel_hi:[0,1]
	v_pk_mul_f32 v[240:241], v[0:1], v[240:241] op_sel_hi:[0,1]
	v_cvt_pk_bf16_f32 v226, v226, v227
	v_cvt_pk_bf16_f32 v227, v228, v229
	v_mul_f32_e32 v182, v170, v181
	v_mul_f32_e32 v183, v169, v181
	global_store_dwordx2 v[184:185], v[226:227], off
	v_cvt_pk_bf16_f32 v226, v236, v237
	v_cvt_pk_bf16_f32 v227, v240, v241
	v_mul_f32_e32 v182, 0.15915494, v182
	v_mul_f32_e32 v183, 0.15915494, v183
	global_store_dwordx2 v[184:185], v[226:227], off offset:64
	v_sin_f32_e32 v225, v182
	v_sin_f32_e32 v226, v183
	v_cos_f32_e32 v227, v182
	v_cos_f32_e32 v228, v183
	v_pk_mul_f32 v[234:235], v[70:71], v[180:181] op_sel_hi:[1,0]
	v_pk_mul_f32 v[238:239], v[66:67], v[180:181] op_sel_hi:[1,0]
	v_pk_mul_f32 v[234:235], v[134:135], v[234:235]
	v_cndmask_b32_e32 v236, 0, v225, vcc
	v_cndmask_b32_e32 v237, 0, v226, vcc
	v_pk_mul_f32 v[238:239], v[130:131], v[238:239]
	v_cndmask_b32_e32 v230, 1.0, v227, vcc
	v_cndmask_b32_e32 v231, 1.0, v228, vcc
	v_pk_mul_f32 v[240:241], v[236:237], v[234:235]
	v_pk_mul_f32 v[236:237], v[236:237], v[238:239]
	v_mul_f32_e32 v182, v168, v181
	v_mul_f32_e32 v181, v149, v181
	v_pk_fma_f32 v[240:241], v[230:231], v[238:239], v[240:241]
	v_pk_fma_f32 v[230:231], v[230:231], v[234:235], v[236:237] neg_lo:[0,0,1] neg_hi:[0,0,1]
	v_mul_f32_e32 v182, 0.15915494, v182
	v_mul_f32_e32 v181, 0.15915494, v181
	v_pk_mul_f32 v[234:235], v[0:1], v[230:231] op_sel_hi:[0,1]
	v_sin_f32_e32 v229, v182
	v_sin_f32_e32 v230, v181
	v_cos_f32_e32 v232, v181
	v_cos_f32_e32 v231, v182
	v_pk_mul_f32 v[238:239], v[72:73], v[180:181] op_sel_hi:[1,0]
	v_cndmask_b32_e32 v243, 0, v230, vcc
	v_pk_mul_f32 v[238:239], v[136:137], v[238:239]
	v_cndmask_b32_e32 v242, 0, v229, vcc
	v_pk_mul_f32 v[180:181], v[68:69], v[180:181] op_sel_hi:[1,0]
	v_cndmask_b32_e32 v237, 1.0, v232, vcc
	v_cndmask_b32_e32 v236, 1.0, v231, vcc
	v_pk_mul_f32 v[180:181], v[132:133], v[180:181]
	v_pk_mul_f32 v[244:245], v[242:243], v[238:239]
	v_pk_mul_f32 v[240:241], v[0:1], v[240:241] op_sel_hi:[0,1]
	v_pk_fma_f32 v[244:245], v[236:237], v[180:181], v[244:245]
	v_pk_mul_f32 v[180:181], v[242:243], v[180:181]
	v_pk_mul_f32 v[244:245], v[0:1], v[244:245] op_sel_hi:[0,1]
	v_pk_fma_f32 v[180:181], v[236:237], v[238:239], v[180:181] neg_lo:[0,0,1] neg_hi:[0,0,1]
	v_cvt_pk_bf16_f32 v234, v234, v235
	v_pk_mul_f32 v[180:181], v[0:1], v[180:181] op_sel_hi:[0,1]
	v_cvt_pk_bf16_f32 v235, v180, v181
	v_cvt_pk_bf16_f32 v180, v240, v241
	v_cvt_pk_bf16_f32 v181, v244, v245
	global_store_dwordx2 v[184:185], v[234:235], off offset:32
	global_store_dwordx2 v[184:185], v[180:181], off offset:96
	v_pk_mul_f32 v[184:185], v[64:65], v[64:65]
	v_pk_mul_f32 v[234:235], v[62:63], v[62:63]
	v_add_u32_e32 v180, 0x80, v160
	v_pk_mov_b32 v[236:237], v[234:235], v[184:185] op_sel:[1,0]
	v_mov_b32_e32 v235, v185
	v_pk_add_f32 v[184:185], v[236:237], v[234:235]
	v_pk_mul_f32 v[234:235], v[56:57], v[56:57]
	v_pk_mul_f32 v[236:237], v[54:55], v[54:55]
	v_ashrrev_i32_e32 v181, 6, v180
	v_pk_add_f32 v[184:185], v[184:185], v[184:185] op_sel_hi:[0,1]
	v_pk_mov_b32 v[238:239], v[236:237], v[234:235] op_sel:[1,0]
	v_mov_b32_e32 v237, v235
	v_cvt_f32_i32_e32 v182, v181
	v_pk_add_f32 v[234:235], v[238:239], v[236:237]
	v_mul_f32_e32 v184, v58, v58
	v_pk_add_f32 v[234:235], v[234:235], v[234:235] op_sel_hi:[0,1]
	v_pk_fma_f32 v[236:237], v[58:59], v[58:59], v[184:185] op_sel_hi:[1,1,0]
	v_mul_f32_e32 v184, v60, v60
	v_pk_fma_f32 v[238:239], v[60:61], v[60:61], v[184:185] op_sel_hi:[1,1,0]
	v_mul_f32_e32 v234, v52, v52
	v_mul_f32_e32 v184, v53, v53
	v_mul_f32_e32 v236, v50, v50
	v_mul_f32_e32 v238, v51, v51
	v_pk_add_f32 v[184:185], v[234:235], v[184:185]
	v_mul_f32_e32 v183, v170, v182
	v_mul_f32_e32 v235, v169, v182
	v_pk_add_f32 v[236:237], v[236:237], v[238:239]
	v_mul_f32_e32 v183, 0.15915494, v183
	v_mul_f32_e32 v235, 0.15915494, v235
	v_pk_add_f32 v[184:185], v[236:237], v[184:185]
	v_cos_f32_e32 v234, v183
	v_sin_f32_e32 v183, v183
	v_cos_f32_e32 v236, v235
	s_movk_i32 s4, 0x3f80
	v_cmp_gt_i32_e32 vcc, s4, v160
	v_sin_f32_e32 v237, v235
	v_pk_mul_f32 v[242:243], v[46:47], v[46:47]
	v_cndmask_b32_e32 v235, 1.0, v236, vcc
	v_cndmask_b32_e32 v236, 0, v183, vcc
	v_mul_f32_e32 v183, v168, v182
	v_mul_f32_e32 v182, v149, v182
	v_mul_f32_e32 v183, 0.15915494, v183
	v_mul_f32_e32 v182, 0.15915494, v182
	v_cos_f32_e32 v238, v182
	v_cos_f32_e32 v240, v183
	v_sin_f32_e32 v183, v183
	v_sin_f32_e32 v182, v182
	v_cndmask_b32_e32 v239, 1.0, v238, vcc
	v_cndmask_b32_e32 v238, 1.0, v240, vcc
	v_pk_mul_f32 v[240:241], v[48:49], v[48:49]
	v_cndmask_b32_e32 v237, 0, v237, vcc
	v_pk_mov_b32 v[244:245], v[242:243], v[240:241] op_sel:[1,0]
	v_mov_b32_e32 v243, v241
	v_pk_add_f32 v[240:241], v[244:245], v[242:243]
	v_pk_mul_f32 v[242:243], v[40:41], v[40:41]
	v_pk_add_f32 v[240:241], v[240:241], v[240:241] op_sel_hi:[0,1]
	v_pk_mul_f32 v[244:245], v[38:39], v[38:39]
	v_mul_f32_e32 v240, v42, v42
	v_pk_mov_b32 v[246:247], v[244:245], v[242:243] op_sel:[1,0]
	v_mov_b32_e32 v245, v243
	v_pk_add_f32 v[242:243], v[246:247], v[244:245]
	v_pk_fma_f32 v[244:245], v[42:43], v[42:43], v[240:241] op_sel_hi:[1,1,0]
	v_mul_f32_e32 v240, v44, v44
	v_pk_add_f32 v[242:243], v[242:243], v[242:243] op_sel_hi:[0,1]
	v_pk_fma_f32 v[246:247], v[44:45], v[44:45], v[240:241] op_sel_hi:[1,1,0]
	v_mul_f32_e32 v244, v34, v34
	v_mul_f32_e32 v246, v35, v35
	v_mul_f32_e32 v242, v36, v36
	v_mul_f32_e32 v240, v37, v37
	v_pk_add_f32 v[244:245], v[244:245], v[246:247]
	v_pk_add_f32 v[240:241], v[242:243], v[240:241]
	v_mov_b32_e32 v243, v184
	v_pk_add_f32 v[240:241], v[244:245], v[240:241]
	v_cndmask_b32_e32 v244, 0, v161, vcc
	v_mov_b32_e32 v242, v240
	v_mov_b32_e32 v184, v241
	v_pk_add_f32 v[184:185], v[242:243], v[184:185]
	ds_bpermute_b32 v241, v172, v185
	ds_bpermute_b32 v240, v172, v184
	v_cndmask_b32_e32 v245, 0, v173, vcc
	v_cndmask_b32_e32 v247, 1.0, v212, vcc
	v_cndmask_b32_e32 v234, 1.0, v234, vcc
	v_cndmask_b32_e32 v243, 0, v182, vcc
	s_waitcnt lgkmcnt(0)
	v_pk_add_f32 v[184:185], v[184:185], v[240:241]
	ds_bpermute_b32 v241, v171, v185
	ds_bpermute_b32 v240, v171, v184
	v_cndmask_b32_e32 v242, 0, v183, vcc
	v_ashrrev_i32_e32 v181, 31, v180
	v_lshlrev_b64 v[180:181], s2, v[180:181]
	v_lshl_add_u64 v[180:181], v[180:181], 1, v[164:165]
	s_waitcnt lgkmcnt(0)
	v_pk_add_f32 v[184:185], v[184:185], v[240:241]
	v_cndmask_b32_e32 v174, 1.0, v174, vcc
	v_pk_fma_f32 v[184:185], v[184:185], s[6:7], v[166:167] op_sel_hi:[1,0,0]
	v_cndmask_b32_e32 v175, 1.0, v175, vcc
	v_mul_f32_e32 v161, 0x4b800000, v185
	v_cmp_gt_f32_e64 s[4:5], s3, v185
	v_cndmask_b32_e32 v246, 1.0, v210, vcc
	v_cndmask_b32_e32 v211, 0, v211, vcc
	v_cndmask_b32_e64 v161, v185, v161, s[4:5]
	v_rsq_f32_e32 v161, v161
	v_cndmask_b32_e32 v210, 0, v209, vcc
	v_cmp_gt_f32_e32 vcc, s3, v184
	v_add_u32_e32 v240, 0x90, v160
	v_mul_f32_e32 v173, 0x45800000, v161
	v_cndmask_b32_e64 v212, v161, v173, s[4:5]
	v_pk_mul_f32 v[248:249], v[62:63], v[212:213] op_sel_hi:[1,0]
	v_pk_mul_f32 v[250:251], v[58:59], v[212:213] op_sel_hi:[1,0]
	v_pk_mul_f32 v[248:249], v[142:143], v[248:249]
	v_pk_mul_f32 v[250:251], v[138:139], v[250:251]
	v_pk_mul_f32 v[182:183], v[236:237], v[248:249]
	v_pk_mul_f32 v[236:237], v[236:237], v[250:251]
	v_pk_fma_f32 v[182:183], v[234:235], v[250:251], v[182:183]
	v_pk_fma_f32 v[234:235], v[234:235], v[248:249], v[236:237] neg_lo:[0,0,1] neg_hi:[0,0,1]
	v_pk_mul_f32 v[236:237], v[64:65], v[212:213] op_sel_hi:[1,0]
	v_pk_mul_f32 v[248:249], v[60:61], v[212:213] op_sel_hi:[1,0]
	v_pk_mul_f32 v[236:237], v[144:145], v[236:237]
	v_pk_mul_f32 v[248:249], v[140:141], v[248:249]
	v_pk_mul_f32 v[250:251], v[242:243], v[236:237]
	v_pk_mul_f32 v[242:243], v[242:243], v[248:249]
	v_pk_fma_f32 v[250:251], v[238:239], v[248:249], v[250:251]
	v_pk_mul_f32 v[182:183], v[0:1], v[182:183] op_sel_hi:[0,1]
	v_pk_mul_f32 v[250:251], v[0:1], v[250:251] op_sel_hi:[0,1]
	v_pk_fma_f32 v[236:237], v[238:239], v[236:237], v[242:243] neg_lo:[0,0,1] neg_hi:[0,0,1]
	v_pk_mul_f32 v[234:235], v[0:1], v[234:235] op_sel_hi:[0,1]
	v_pk_mul_f32 v[236:237], v[0:1], v[236:237] op_sel_hi:[0,1]
	v_cvt_pk_bf16_f32 v182, v182, v183
	v_cvt_pk_bf16_f32 v183, v250, v251
	v_cvt_pk_bf16_f32 v234, v234, v235
	v_cvt_pk_bf16_f32 v235, v236, v237
	global_store_dwordx2 v[180:181], v[182:183], off offset:64
	v_pk_mul_f32 v[182:183], v[54:55], v[212:213] op_sel_hi:[1,0]
	global_store_dwordx2 v[180:181], v[234:235], off
	v_pk_mul_f32 v[182:183], v[134:135], v[182:183]
	v_pk_mul_f32 v[234:235], v[50:51], v[212:213] op_sel_hi:[1,0]
	v_pk_mul_f32 v[236:237], v[244:245], v[182:183]
	v_pk_mul_f32 v[234:235], v[130:131], v[234:235]
	v_mul_f32_e32 v161, 0x4b800000, v184
	v_pk_fma_f32 v[236:237], v[174:175], v[234:235], v[236:237]
	v_pk_mul_f32 v[234:235], v[244:245], v[234:235]
	v_cndmask_b32_e32 v161, v184, v161, vcc
	v_pk_fma_f32 v[174:175], v[174:175], v[182:183], v[234:235] neg_lo:[0,0,1] neg_hi:[0,0,1]
	v_pk_mul_f32 v[182:183], v[56:57], v[212:213] op_sel_hi:[1,0]
	v_pk_mul_f32 v[234:235], v[52:53], v[212:213] op_sel_hi:[1,0]
	v_pk_mul_f32 v[182:183], v[136:137], v[182:183]
	v_pk_mul_f32 v[234:235], v[132:133], v[234:235]
	v_pk_mul_f32 v[238:239], v[210:211], v[182:183]
	v_pk_mul_f32 v[210:211], v[210:211], v[234:235]
	v_rsq_f32_e32 v161, v161
	v_pk_fma_f32 v[182:183], v[246:247], v[182:183], v[210:211] neg_lo:[0,0,1] neg_hi:[0,0,1]
	v_pk_mul_f32 v[174:175], v[0:1], v[174:175] op_sel_hi:[0,1]
	v_pk_fma_f32 v[238:239], v[246:247], v[234:235], v[238:239]
	v_pk_mul_f32 v[182:183], v[0:1], v[182:183] op_sel_hi:[0,1]
	v_pk_mul_f32 v[236:237], v[0:1], v[236:237] op_sel_hi:[0,1]
	v_pk_mul_f32 v[238:239], v[0:1], v[238:239] op_sel_hi:[0,1]
	v_cvt_pk_bf16_f32 v174, v174, v175
	v_cvt_pk_bf16_f32 v175, v182, v183
	global_store_dwordx2 v[180:181], v[174:175], off offset:32
	v_cvt_pk_bf16_f32 v174, v236, v237
	v_cvt_pk_bf16_f32 v175, v238, v239
	v_mul_f32_e32 v173, 0x45800000, v161
	global_store_dwordx2 v[180:181], v[174:175], off offset:96
	v_cndmask_b32_e32 v174, v161, v173, vcc
	v_ashrrev_i32_e32 v161, 6, v240
	v_cvt_f32_i32_e32 v161, v161
	s_movk_i32 s4, 0x3f70
	v_cmp_gt_i32_e32 vcc, s4, v160
	v_ashrrev_i32_e32 v241, 31, v240
	v_mul_f32_e32 v173, v170, v161
	v_mul_f32_e32 v173, 0.15915494, v173
	v_mul_f32_e32 v182, v169, v161
	v_cos_f32_e32 v175, v173
	v_sin_f32_e32 v173, v173
	v_mul_f32_e32 v182, 0.15915494, v182
	v_sin_f32_e32 v209, v182
	v_cos_f32_e32 v183, v182
	v_pk_mul_f32 v[184:185], v[46:47], v[174:175] op_sel_hi:[1,0]
	v_cndmask_b32_e32 v210, 0, v173, vcc
	v_pk_mul_f32 v[234:235], v[42:43], v[174:175] op_sel_hi:[1,0]
	v_mul_f32_e32 v173, v168, v161
	v_mul_f32_e32 v161, v149, v161
	v_pk_mul_f32 v[184:185], v[142:143], v[184:185]
	v_cndmask_b32_e32 v211, 0, v209, vcc
	v_pk_mul_f32 v[234:235], v[138:139], v[234:235]
	v_mul_f32_e32 v161, 0.15915494, v161
	v_cndmask_b32_e32 v182, 1.0, v175, vcc
	v_cndmask_b32_e32 v183, 1.0, v183, vcc
	v_pk_mul_f32 v[236:237], v[210:211], v[184:185]
	v_pk_mul_f32 v[210:211], v[210:211], v[234:235]
	v_mul_f32_e32 v173, 0.15915494, v173
	v_cos_f32_e32 v175, v161
	v_pk_fma_f32 v[236:237], v[182:183], v[234:235], v[236:237]
	v_pk_fma_f32 v[182:183], v[182:183], v[184:185], v[210:211] neg_lo:[0,0,1] neg_hi:[0,0,1]
	v_cos_f32_e32 v184, v173
	v_sin_f32_e32 v173, v173
	v_sin_f32_e32 v161, v161
	v_pk_mul_f32 v[210:211], v[48:49], v[174:175] op_sel_hi:[1,0]
	v_pk_mul_f32 v[238:239], v[44:45], v[174:175] op_sel_hi:[1,0]
	v_pk_mul_f32 v[210:211], v[144:145], v[210:211]
	v_cndmask_b32_e32 v235, 0, v161, vcc
	v_cndmask_b32_e32 v234, 0, v173, vcc
	v_pk_mul_f32 v[238:239], v[140:141], v[238:239]
	v_lshlrev_b64 v[180:181], s2, v[240:241]
	v_cndmask_b32_e32 v185, 1.0, v175, vcc
	v_cndmask_b32_e32 v184, 1.0, v184, vcc
	v_pk_mul_f32 v[240:241], v[234:235], v[210:211]
	v_pk_mul_f32 v[234:235], v[234:235], v[238:239]
	v_pk_fma_f32 v[240:241], v[184:185], v[238:239], v[240:241]
	v_pk_fma_f32 v[184:185], v[184:185], v[210:211], v[234:235] neg_lo:[0,0,1] neg_hi:[0,0,1]
	v_pk_mul_f32 v[182:183], v[0:1], v[182:183] op_sel_hi:[0,1]
	v_pk_mul_f32 v[184:185], v[0:1], v[184:185] op_sel_hi:[0,1]
	v_lshl_add_u64 v[180:181], v[180:181], 1, v[164:165]
	v_pk_mul_f32 v[236:237], v[0:1], v[236:237] op_sel_hi:[0,1]
	v_pk_mul_f32 v[240:241], v[0:1], v[240:241] op_sel_hi:[0,1]
	v_cvt_pk_bf16_f32 v182, v182, v183
	v_cvt_pk_bf16_f32 v183, v184, v185
	v_pk_mul_f32 v[184:185], v[38:39], v[174:175] op_sel_hi:[1,0]
	v_cndmask_b32_e32 v210, 0, v213, vcc
	v_pk_mul_f32 v[212:213], v[34:35], v[174:175] op_sel_hi:[1,0]
	global_store_dwordx2 v[180:181], v[182:183], off
	v_cvt_pk_bf16_f32 v182, v236, v237
	v_cvt_pk_bf16_f32 v183, v240, v241
	v_pk_mul_f32 v[184:185], v[134:135], v[184:185]
	v_cndmask_b32_e32 v211, 0, v214, vcc
	v_pk_mul_f32 v[212:213], v[130:131], v[212:213]
	global_store_dwordx2 v[180:181], v[182:183], off offset:64
	v_cndmask_b32_e32 v182, 1.0, v215, vcc
	v_cndmask_b32_e32 v183, 1.0, v216, vcc
	v_pk_mul_f32 v[214:215], v[210:211], v[184:185]
	v_pk_mul_f32 v[210:211], v[210:211], v[212:213]
	v_pk_fma_f32 v[214:215], v[182:183], v[212:213], v[214:215]
	v_pk_fma_f32 v[182:183], v[182:183], v[184:185], v[210:211] neg_lo:[0,0,1] neg_hi:[0,0,1]
	v_pk_mul_f32 v[210:211], v[40:41], v[174:175] op_sel_hi:[1,0]
	v_cndmask_b32_e32 v213, 0, v218, vcc
	v_pk_mul_f32 v[210:211], v[136:137], v[210:211]
	v_cndmask_b32_e32 v212, 0, v217, vcc
	v_pk_mul_f32 v[174:175], v[36:37], v[174:175] op_sel_hi:[1,0]
	v_cndmask_b32_e32 v185, 1.0, v220, vcc
	v_cndmask_b32_e32 v184, 1.0, v219, vcc
	v_pk_mul_f32 v[174:175], v[132:133], v[174:175]
	v_pk_mul_f32 v[216:217], v[212:213], v[210:211]
	v_pk_mul_f32 v[214:215], v[0:1], v[214:215] op_sel_hi:[0,1]
	v_pk_fma_f32 v[216:217], v[184:185], v[174:175], v[216:217]
	v_pk_mul_f32 v[174:175], v[212:213], v[174:175]
	v_pk_mul_f32 v[182:183], v[0:1], v[182:183] op_sel_hi:[0,1]
	v_pk_fma_f32 v[174:175], v[184:185], v[210:211], v[174:175] neg_lo:[0,0,1] neg_hi:[0,0,1]
	v_pk_mul_f32 v[216:217], v[0:1], v[216:217] op_sel_hi:[0,1]
	v_pk_mul_f32 v[174:175], v[0:1], v[174:175] op_sel_hi:[0,1]
	v_cvt_pk_bf16_f32 v182, v182, v183
	v_cvt_pk_bf16_f32 v183, v174, v175
	v_cvt_pk_bf16_f32 v174, v214, v215
	v_cvt_pk_bf16_f32 v175, v216, v217
	global_store_dwordx2 v[180:181], v[182:183], off offset:32
	global_store_dwordx2 v[180:181], v[174:175], off offset:96
	v_pk_mul_f32 v[180:181], v[32:33], v[32:33]
	v_pk_mul_f32 v[182:183], v[30:31], v[30:31]
	v_add_u32_e32 v174, 0xa0, v160
	v_pk_mov_b32 v[184:185], v[182:183], v[180:181] op_sel:[1,0]
	v_mov_b32_e32 v183, v181
	v_pk_add_f32 v[180:181], v[184:185], v[182:183]
	v_pk_mul_f32 v[182:183], v[24:25], v[24:25]
	v_pk_mul_f32 v[184:185], v[22:23], v[22:23]
	v_ashrrev_i32_e32 v161, 6, v174
	v_pk_add_f32 v[180:181], v[180:181], v[180:181] op_sel_hi:[0,1]
	v_pk_mov_b32 v[210:211], v[184:185], v[182:183] op_sel:[1,0]
	v_mov_b32_e32 v185, v183
	v_cvt_f32_i32_e32 v161, v161
	v_pk_mul_f32 v[212:213], v[16:17], v[16:17]
	v_pk_mul_f32 v[214:215], v[14:15], v[14:15]
	v_pk_add_f32 v[182:183], v[210:211], v[184:185]
	v_mul_f32_e32 v180, v26, v26
	v_pk_mov_b32 v[216:217], v[214:215], v[212:213] op_sel:[1,0]
	v_mov_b32_e32 v215, v213
	v_pk_add_f32 v[182:183], v[182:183], v[182:183] op_sel_hi:[0,1]
	v_pk_fma_f32 v[184:185], v[26:27], v[26:27], v[180:181] op_sel_hi:[1,1,0]
	v_mul_f32_e32 v180, v28, v28
	v_pk_add_f32 v[212:213], v[216:217], v[214:215]
	v_pk_fma_f32 v[210:211], v[28:29], v[28:29], v[180:181] op_sel_hi:[1,1,0]
	v_mul_f32_e32 v182, v20, v20
	v_mul_f32_e32 v180, v21, v21
	v_pk_add_f32 v[212:213], v[212:213], v[212:213] op_sel_hi:[0,1]
	v_pk_mul_f32 v[214:215], v[8:9], v[8:9]
	v_pk_mul_f32 v[216:217], v[6:7], v[6:7]
	v_mul_f32_e32 v184, v18, v18
	v_mul_f32_e32 v210, v19, v19
	v_pk_add_f32 v[180:181], v[182:183], v[180:181]
	v_mul_f32_e32 v173, v170, v161
	v_mul_f32_e32 v183, v169, v161
	v_pk_mov_b32 v[218:219], v[216:217], v[214:215] op_sel:[1,0]
	v_mov_b32_e32 v217, v215
	v_mul_f32_e32 v212, v10, v10
	v_pk_add_f32 v[184:185], v[184:185], v[210:211]
	v_mul_f32_e32 v173, 0.15915494, v173
	v_mul_f32_e32 v183, 0.15915494, v183
	v_pk_add_f32 v[214:215], v[218:219], v[216:217]
	v_pk_fma_f32 v[216:217], v[10:11], v[10:11], v[212:213] op_sel_hi:[1,1,0]
	v_mul_f32_e32 v212, v12, v12
	v_pk_add_f32 v[180:181], v[184:185], v[180:181]
	v_cos_f32_e32 v182, v173
	v_sin_f32_e32 v173, v173
	v_cos_f32_e32 v184, v183
	v_pk_add_f32 v[214:215], v[214:215], v[214:215] op_sel_hi:[0,1]
	v_pk_fma_f32 v[218:219], v[12:13], v[12:13], v[212:213] op_sel_hi:[1,1,0]
	v_mul_f32_e32 v216, v2, v2
	v_mul_f32_e32 v218, v3, v3
	v_mul_f32_e32 v214, v4, v4
	v_mul_f32_e32 v212, v5, v5
	s_movk_i32 s4, 0x3f60
	v_pk_add_f32 v[216:217], v[216:217], v[218:219]
	v_pk_add_f32 v[212:213], v[214:215], v[212:213]
	v_cmp_gt_i32_e32 vcc, s4, v160
	v_pk_add_f32 v[212:213], v[216:217], v[212:213]
	v_sin_f32_e32 v185, v183
	v_cndmask_b32_e32 v183, 1.0, v184, vcc
	v_cndmask_b32_e32 v184, 0, v173, vcc
	v_mul_f32_e32 v173, v168, v161
	v_mov_b32_e32 v214, v212
	v_mov_b32_e32 v215, v180
	v_mov_b32_e32 v180, v213
	v_mul_f32_e32 v173, 0.15915494, v173
	v_pk_add_f32 v[180:181], v[214:215], v[180:181]
	v_cos_f32_e32 v210, v173
	v_sin_f32_e32 v220, v173
	ds_bpermute_b32 v173, v172, v181
	ds_bpermute_b32 v172, v172, v180
	v_mul_f32_e32 v161, v149, v161
	v_mul_f32_e32 v161, 0.15915494, v161
	v_cos_f32_e32 v209, v161
	v_sin_f32_e32 v161, v161
	s_waitcnt lgkmcnt(0)
	v_pk_add_f32 v[172:173], v[180:181], v[172:173]
	ds_bpermute_b32 v181, v171, v173
	ds_bpermute_b32 v180, v171, v172
	v_cndmask_b32_e32 v213, 0, v161, vcc
	v_cndmask_b32_e32 v212, 0, v220, vcc
	v_cndmask_b32_e32 v185, 0, v185, vcc
	v_cndmask_b32_e32 v182, 1.0, v182, vcc
	s_waitcnt lgkmcnt(0)
	v_pk_add_f32 v[172:173], v[172:173], v[180:181]
	v_cndmask_b32_e32 v215, 1.0, v208, vcc
	v_pk_fma_f32 v[166:167], v[172:173], s[6:7], v[166:167] op_sel_hi:[1,0,0]
	v_cndmask_b32_e32 v172, 0, v221, vcc
	v_mul_f32_e32 v161, 0x4b800000, v167
	v_cmp_gt_f32_e64 s[4:5], s3, v167
	v_cndmask_b32_e32 v208, 1.0, v223, vcc
	v_cndmask_b32_e32 v173, 0, v222, vcc
	v_cndmask_b32_e64 v161, v167, v161, s[4:5]
	v_rsq_f32_e32 v161, v161
	v_cndmask_b32_e32 v211, 1.0, v209, vcc
	v_cndmask_b32_e32 v210, 1.0, v210, vcc
	v_ashrrev_i32_e32 v175, 31, v174
	v_mul_f32_e32 v167, 0x45800000, v161
	v_cndmask_b32_e64 v216, v161, v167, s[4:5]
	v_pk_mul_f32 v[218:219], v[30:31], v[216:217] op_sel_hi:[1,0]
	v_pk_mul_f32 v[220:221], v[26:27], v[216:217] op_sel_hi:[1,0]
	v_pk_mul_f32 v[218:219], v[142:143], v[218:219]
	v_pk_mul_f32 v[220:221], v[138:139], v[220:221]
	v_pk_mul_f32 v[222:223], v[184:185], v[218:219]
	v_pk_mul_f32 v[184:185], v[184:185], v[220:221]
	v_pk_fma_f32 v[222:223], v[182:183], v[220:221], v[222:223]
	v_pk_fma_f32 v[182:183], v[182:183], v[218:219], v[184:185] neg_lo:[0,0,1] neg_hi:[0,0,1]
	v_pk_mul_f32 v[184:185], v[32:33], v[216:217] op_sel_hi:[1,0]
	v_pk_mul_f32 v[218:219], v[28:29], v[216:217] op_sel_hi:[1,0]
	v_pk_mul_f32 v[184:185], v[144:145], v[184:185]
	v_pk_mul_f32 v[218:219], v[140:141], v[218:219]
	v_pk_mul_f32 v[220:221], v[212:213], v[184:185]
	v_pk_mul_f32 v[212:213], v[212:213], v[218:219]
	v_lshlrev_b64 v[174:175], s2, v[174:175]
	v_pk_fma_f32 v[184:185], v[210:211], v[184:185], v[212:213] neg_lo:[0,0,1] neg_hi:[0,0,1]
	v_pk_mul_f32 v[182:183], v[0:1], v[182:183] op_sel_hi:[0,1]
	v_pk_fma_f32 v[220:221], v[210:211], v[218:219], v[220:221]
	v_pk_mul_f32 v[184:185], v[0:1], v[184:185] op_sel_hi:[0,1]
	v_lshl_add_u64 v[174:175], v[174:175], 1, v[164:165]
	v_pk_mul_f32 v[222:223], v[0:1], v[222:223] op_sel_hi:[0,1]
	v_pk_mul_f32 v[220:221], v[0:1], v[220:221] op_sel_hi:[0,1]
	v_cvt_pk_bf16_f32 v182, v182, v183
	v_cvt_pk_bf16_f32 v183, v184, v185
	global_store_dwordx2 v[174:175], v[182:183], off
	v_cvt_pk_bf16_f32 v182, v222, v223
	v_cvt_pk_bf16_f32 v183, v220, v221
	global_store_dwordx2 v[174:175], v[182:183], off offset:64
	v_pk_mul_f32 v[182:183], v[22:23], v[216:217] op_sel_hi:[1,0]
	v_pk_mul_f32 v[184:185], v[18:19], v[216:217] op_sel_hi:[1,0]
	v_cndmask_b32_e32 v176, 0, v176, vcc
	v_cndmask_b32_e32 v177, 0, v177, vcc
	v_pk_mul_f32 v[182:183], v[134:135], v[182:183]
	v_pk_mul_f32 v[184:185], v[130:131], v[184:185]
	v_cndmask_b32_e32 v214, 1.0, v207, vcc
	v_pk_mul_f32 v[210:211], v[176:177], v[182:183]
	v_pk_mul_f32 v[176:177], v[176:177], v[184:185]
	v_cndmask_b32_e32 v209, 1.0, v224, vcc
	v_pk_fma_f32 v[176:177], v[214:215], v[182:183], v[176:177] neg_lo:[0,0,1] neg_hi:[0,0,1]
	v_pk_mul_f32 v[182:183], v[24:25], v[216:217] op_sel_hi:[1,0]
	v_mul_f32_e32 v161, 0x4b800000, v166
	v_cmp_gt_f32_e32 vcc, s3, v166
	v_pk_fma_f32 v[210:211], v[214:215], v[184:185], v[210:211]
	v_pk_mul_f32 v[182:183], v[136:137], v[182:183]
	v_pk_mul_f32 v[184:185], v[20:21], v[216:217] op_sel_hi:[1,0]
	v_cndmask_b32_e32 v161, v166, v161, vcc
	v_pk_mul_f32 v[184:185], v[132:133], v[184:185]
	v_pk_mul_f32 v[212:213], v[172:173], v[182:183]
	v_rsq_f32_e32 v161, v161
	v_pk_fma_f32 v[212:213], v[208:209], v[184:185], v[212:213]
	v_pk_mul_f32 v[210:211], v[0:1], v[210:211] op_sel_hi:[0,1]
	v_pk_mul_f32 v[212:213], v[0:1], v[212:213] op_sel_hi:[0,1]
	v_cvt_pk_bf16_f32 v166, v210, v211
	v_cvt_pk_bf16_f32 v167, v212, v213
	v_add_u32_e32 v180, 0xb0, v160
	global_store_dwordx2 v[174:175], v[166:167], off offset:96
	v_mul_f32_e32 v166, 0x45800000, v161
	v_cndmask_b32_e32 v166, v161, v166, vcc
	v_ashrrev_i32_e32 v161, 6, v180
	v_cvt_f32_i32_e32 v161, v161
	v_pk_mul_f32 v[172:173], v[172:173], v[184:185]
	v_pk_mul_f32 v[176:177], v[0:1], v[176:177] op_sel_hi:[0,1]
	v_pk_fma_f32 v[172:173], v[208:209], v[182:183], v[172:173] neg_lo:[0,0,1] neg_hi:[0,0,1]
	v_mul_f32_e32 v167, v170, v161
	v_mul_f32_e32 v167, 0.15915494, v167
	v_mul_f32_e32 v169, v169, v161
	v_cos_f32_e32 v170, v167
	v_sin_f32_e32 v167, v167
	v_mul_f32_e32 v169, 0.15915494, v169
	v_cos_f32_e32 v171, v169
	v_sin_f32_e32 v169, v169
	v_pk_mul_f32 v[172:173], v[0:1], v[172:173] op_sel_hi:[0,1]
	v_ashrrev_i32_e32 v181, 31, v180
	v_cvt_pk_bf16_f32 v176, v176, v177
	v_cvt_pk_bf16_f32 v177, v172, v173
	v_lshlrev_b64 v[172:173], s2, v[180:181]
	s_movk_i32 s2, 0x3f50
	v_lshl_add_u64 v[164:165], v[172:173], 1, v[164:165]
	v_cmp_gt_i32_e32 vcc, s2, v160
	v_pk_mul_f32 v[172:173], v[14:15], v[166:167] op_sel_hi:[1,0]
	global_store_dwordx2 v[174:175], v[176:177], off offset:32
	v_pk_mul_f32 v[142:143], v[142:143], v[172:173]
	v_cndmask_b32_e32 v172, 0, v167, vcc
	v_cndmask_b32_e32 v173, 0, v169, vcc
	v_pk_mul_f32 v[174:175], v[10:11], v[166:167] op_sel_hi:[1,0]
	v_cndmask_b32_e32 v170, 1.0, v170, vcc
	v_cndmask_b32_e32 v171, 1.0, v171, vcc
	v_pk_mul_f32 v[138:139], v[138:139], v[174:175]
	v_pk_mul_f32 v[174:175], v[172:173], v[142:143]
	s_mov_b64 s[28:29], 0
	v_pk_fma_f32 v[174:175], v[170:171], v[138:139], v[174:175]
	v_pk_mul_f32 v[138:139], v[172:173], v[138:139]
	v_pk_mul_f32 v[174:175], v[0:1], v[174:175] op_sel_hi:[0,1]
	v_pk_fma_f32 v[138:139], v[170:171], v[142:143], v[138:139] neg_lo:[0,0,1] neg_hi:[0,0,1]
	v_mul_f32_e32 v142, v168, v161
	v_mul_f32_e32 v142, 0.15915494, v142
	v_mul_f32_e32 v143, v149, v161
	v_mul_f32_e32 v143, 0.15915494, v143
	v_sin_f32_e32 v167, v142
	v_sin_f32_e32 v170, v143
	v_cos_f32_e32 v149, v143
	v_cos_f32_e32 v161, v142
	v_pk_mul_f32 v[168:169], v[16:17], v[166:167] op_sel_hi:[1,0]
	v_pk_mul_f32 v[138:139], v[0:1], v[138:139] op_sel_hi:[0,1]
	v_pk_mul_f32 v[144:145], v[144:145], v[168:169]
	v_cndmask_b32_e32 v169, 0, v170, vcc
	v_cndmask_b32_e32 v168, 0, v167, vcc
	v_pk_mul_f32 v[170:171], v[12:13], v[166:167] op_sel_hi:[1,0]
	v_cndmask_b32_e32 v143, 1.0, v149, vcc
	v_cndmask_b32_e32 v142, 1.0, v161, vcc
	v_pk_mul_f32 v[140:141], v[140:141], v[170:171]
	v_pk_mul_f32 v[170:171], v[168:169], v[144:145]
	v_cvt_pk_bf16_f32 v138, v138, v139
	v_pk_fma_f32 v[170:171], v[142:143], v[140:141], v[170:171]
	v_pk_mul_f32 v[140:141], v[168:169], v[140:141]
	v_pk_mul_f32 v[170:171], v[0:1], v[170:171] op_sel_hi:[0,1]
	v_pk_fma_f32 v[140:141], v[142:143], v[144:145], v[140:141] neg_lo:[0,0,1] neg_hi:[0,0,1]
	v_pk_mul_f32 v[142:143], v[2:3], v[166:167] op_sel_hi:[1,0]
	v_pk_mul_f32 v[140:141], v[0:1], v[140:141] op_sel_hi:[0,1]
	v_cvt_pk_bf16_f32 v139, v140, v141
	v_pk_mul_f32 v[140:141], v[6:7], v[166:167] op_sel_hi:[1,0]
	global_store_dwordx2 v[164:165], v[138:139], off
	v_cvt_pk_bf16_f32 v138, v174, v175
	v_cvt_pk_bf16_f32 v139, v170, v171
	v_pk_mul_f32 v[134:135], v[134:135], v[140:141]
	v_cndmask_b32_e32 v140, 0, v225, vcc
	v_cndmask_b32_e32 v141, 0, v226, vcc
	global_store_dwordx2 v[164:165], v[138:139], off offset:64
	v_cndmask_b32_e32 v138, 1.0, v227, vcc
	v_cndmask_b32_e32 v139, 1.0, v228, vcc
	v_pk_mul_f32 v[130:131], v[130:131], v[142:143]
	v_pk_mul_f32 v[142:143], v[140:141], v[134:135]
	s_nop 0
	v_pk_fma_f32 v[142:143], v[138:139], v[130:131], v[142:143]
	v_pk_mul_f32 v[130:131], v[140:141], v[130:131]
	v_pk_mul_f32 v[140:141], v[4:5], v[166:167] op_sel_hi:[1,0]
	v_pk_fma_f32 v[130:131], v[138:139], v[134:135], v[130:131] neg_lo:[0,0,1] neg_hi:[0,0,1]
	v_pk_mul_f32 v[138:139], v[8:9], v[166:167] op_sel_hi:[1,0]
	v_cndmask_b32_e32 v135, 1.0, v232, vcc
	v_pk_mul_f32 v[136:137], v[136:137], v[138:139]
	v_cndmask_b32_e32 v139, 0, v230, vcc
	v_cndmask_b32_e32 v138, 0, v229, vcc
	v_cndmask_b32_e32 v134, 1.0, v231, vcc
	v_pk_mul_f32 v[132:133], v[132:133], v[140:141]
	v_pk_mul_f32 v[140:141], v[138:139], v[136:137]
	v_pk_mul_f32 v[130:131], v[0:1], v[130:131] op_sel_hi:[0,1]
	v_pk_fma_f32 v[140:141], v[134:135], v[132:133], v[140:141]
	v_pk_mul_f32 v[132:133], v[138:139], v[132:133]
	v_pk_mul_f32 v[142:143], v[0:1], v[142:143] op_sel_hi:[0,1]
	v_pk_fma_f32 v[132:133], v[134:135], v[136:137], v[132:133] neg_lo:[0,0,1] neg_hi:[0,0,1]
	v_pk_mul_f32 v[140:141], v[0:1], v[140:141] op_sel_hi:[0,1]
	v_pk_mul_f32 v[132:133], v[0:1], v[132:133] op_sel_hi:[0,1]
	v_cvt_pk_bf16_f32 v130, v130, v131
	v_cvt_pk_bf16_f32 v131, v132, v133
	global_store_dwordx2 v[164:165], v[130:131], off offset:32
	v_cvt_pk_bf16_f32 v130, v142, v143
	v_cvt_pk_bf16_f32 v131, v140, v141
	global_store_dwordx2 v[164:165], v[130:131], off offset:96

.Latt_fast:
	s_cmp_gt_i32 s65, 3
	s_cselect_b32 s6, 9, 11
	s_cselect_b32 s7, 1.0, 0x3e000000
	s_cselect_b32 s8, 0, s65
	s_lshl_b32 s9, 16, s6
	s_lshl_b32 s28, 0x50, s6
	s_mov_b32 s29, 0
	v_readlane_b32 s2, v253, 38
	v_readlane_b32 s3, v253, 40
	s_cmp_gt_i32 s65, 3
	s_cselect_b32 s2, s3, s2
	v_mov_b32_e32 v176, s2
	ds_read_b64 v[176:177], v176
	v_readlane_b32 s2, v253, 35
	v_readlane_b32 s3, v253, 36
	s_cselect_b32 s2, s3, s2
	v_mov_b32_e32 v174, s2
	ds_read_b64 v[174:175], v174
	v_lshlrev_b32_e32 v172, 4, v203
	v_mov_b32_e32 v173, 0
	s_waitcnt lgkmcnt(1)
	v_lshl_add_u64 v[176:177], v[176:177], 0, v[172:173]
	global_load_dwordx4 v[130:133], v[176:177], off
	global_load_dwordx4 v[134:137], v[176:177], off offset:128
	global_load_dwordx4 v[138:141], v[176:177], off offset:64
	global_load_dwordx4 v[142:145], v[176:177], off offset:192
	v_lshlrev_b32_e32 v161, 2, v203
	v_cvt_f32_i32_e32 v146, v161
	v_add_u32_e32 v147, 1, v161
	v_cvt_f32_i32_e32 v147, v147
	v_add_u32_e32 v148, 2, v161
	v_cvt_f32_i32_e32 v148, v148
	v_add_u32_e32 v149, 3, v161
	v_cvt_f32_i32_e32 v149, v149
	v_mul_f32_e32 v146, 0xbf549a78, v146
	v_mul_f32_e32 v147, 0xbf549a78, v147
	v_mul_f32_e32 v148, 0xbf549a78, v148
	v_mul_f32_e32 v149, 0xbf549a78, v149
	v_exp_f32_e32 v146, v146
	v_exp_f32_e32 v147, v147
	v_exp_f32_e32 v148, v148
	v_exp_f32_e32 v149, v149
	v_mov_b32_e32 v162, 0x3e22f983
	v_mov_b32_e32 v163, 0x3e22f983
	v_mov_b32_e32 v164, s7
	v_mov_b32_e32 v165, s7
	s_lshl_b32 s8, s8, 8
	s_lshl_b32 s2, s30, 6
	s_add_i32 s8, s8, s2
	v_and_b32_e32 v172, 1, v203
	v_lshrrev_b32_e32 v173, 1, v203
	v_lshlrev_b32_e32 v172, 4, v172
	v_lshl_add_u32 v172, v173, 3, v172
	v_add_u32_e32 v172, s8, v172
	v_lshlrev_b32_e32 v172, 1, v172
	v_lshlrev_b32_e32 v173, s6, v160
	v_add_u32_e32 v172, v172, v173
	v_mov_b32_e32 v173, 0
	s_waitcnt lgkmcnt(0)
	v_lshl_add_u64 v[172:173], v[174:175], 0, v[172:173]
	s_mov_b32 s2, s9
	s_mov_b32 s3, 0
	s_cmp_lt_i32 s66, 64
	s_cselect_b32 s8, 1.0, 0
	v_mov_b32_e32 v161, 0x358637bd
	s_waitcnt vmcnt(0)
	v_pk_mul_f32 v[174:175], v[126:127], v[126:127]
	v_pk_fma_f32 v[174:175], v[128:129], v[128:129], v[174:175]
	v_pk_fma_f32 v[174:175], v[118:119], v[118:119], v[174:175]
	v_pk_fma_f32 v[174:175], v[120:121], v[120:121], v[174:175]
	v_pk_fma_f32 v[174:175], v[122:123], v[122:123], v[174:175]
	v_pk_fma_f32 v[174:175], v[124:125], v[124:125], v[174:175]
	v_pk_fma_f32 v[174:175], v[114:115], v[114:115], v[174:175]
	v_pk_fma_f32 v[174:175], v[116:117], v[116:117], v[174:175]
	v_add_f32_e32 v174, v174, v175
	v_mov_b32_e32 v175, v174
	v_mov_b32_e32 v166, v160
	v_lshrrev_b32_e32 v166, 6, v166
	v_permlane16_swap_b32_e32 v175, v174
	v_add_f32_e32 v174, v174, v175
	v_mov_b32_e32 v175, v174
	v_cvt_f32_i32_e32 v166, v166
	v_mul_f32_e32 v166, s8, v166
	v_permlane32_swap_b32_e32 v175, v174
	v_add_f32_e32 v174, v174, v175
	v_fmamk_f32 v174, v174, 0x3c800000, v161
	v_rsq_f32_e32 v170, v174
	v_mov_b32_e32 v168, v160
	v_and_b32_e32 v168, 63, v168
	v_cvt_f32_i32_e32 v168, v168
	v_mul_f32_e32 v168, s8, v168
	v_pk_mul_f32 v[236:237], v[146:147], v[166:167] op_sel_hi:[1,0]
	v_pk_mul_f32 v[236:237], v[236:237], v[162:163]
	v_sin_f32_e32 v244, v236
	v_pk_mul_f32 v[238:239], v[148:149], v[166:167] op_sel_hi:[1,0]
	v_sin_f32_e32 v245, v237
	v_pk_mul_f32 v[238:239], v[238:239], v[162:163]
	v_sin_f32_e32 v246, v238
	v_pk_mul_f32 v[240:241], v[146:147], v[168:169] op_sel_hi:[1,0]
	v_sin_f32_e32 v247, v239
	v_pk_mul_f32 v[240:241], v[240:241], v[162:163]
	v_sin_f32_e32 v248, v240
	v_pk_mul_f32 v[242:243], v[148:149], v[168:169] op_sel_hi:[1,0]
	v_sin_f32_e32 v249, v241
	v_pk_mul_f32 v[242:243], v[242:243], v[162:163]
	v_sin_f32_e32 v250, v242
	v_pk_mul_f32 v[244:245], v[244:245], v[164:165]
	v_sin_f32_e32 v251, v243
	v_pk_mul_f32 v[246:247], v[246:247], v[164:165]
	v_cos_f32_e32 v236, v236
	v_pk_mul_f32 v[248:249], v[248:249], v[164:165]
	v_cos_f32_e32 v237, v237
	v_pk_mul_f32 v[250:251], v[250:251], v[164:165]
	v_cos_f32_e32 v238, v238
	v_pk_mul_f32 v[236:237], v[236:237], v[164:165]
	v_cos_f32_e32 v239, v239
	v_pk_mul_f32 v[206:207], v[126:127], v[170:171] op_sel_hi:[1,0]
	v_cos_f32_e32 v240, v240
	v_pk_mul_f32 v[238:239], v[238:239], v[164:165]
	v_cos_f32_e32 v241, v241
	v_pk_mul_f32 v[206:207], v[206:207], v[130:131]
	v_cos_f32_e32 v242, v242
	v_pk_mul_f32 v[240:241], v[240:241], v[164:165]
	v_cos_f32_e32 v243, v243
	v_pk_mul_f32 v[208:209], v[128:129], v[170:171] op_sel_hi:[1,0]
	v_pk_mul_f32 v[242:243], v[242:243], v[164:165]
	v_pk_mul_f32 v[208:209], v[208:209], v[132:133]
	v_pk_mul_f32 v[214:215], v[122:123], v[170:171] op_sel_hi:[1,0]
	v_pk_mul_f32 v[214:215], v[214:215], v[138:139]
	v_pk_mul_f32 v[216:217], v[124:125], v[170:171] op_sel_hi:[1,0]
	v_pk_mul_f32 v[216:217], v[216:217], v[140:141]
	v_pk_mul_f32 v[210:211], v[118:119], v[170:171] op_sel_hi:[1,0]
	v_pk_mul_f32 v[210:211], v[210:211], v[134:135]
	v_pk_mul_f32 v[212:213], v[120:121], v[170:171] op_sel_hi:[1,0]
	v_pk_mul_f32 v[212:213], v[212:213], v[136:137]
	v_pk_mul_f32 v[218:219], v[114:115], v[170:171] op_sel_hi:[1,0]
	v_pk_mul_f32 v[218:219], v[218:219], v[142:143]
	v_pk_mul_f32 v[220:221], v[116:117], v[170:171] op_sel_hi:[1,0]
	v_pk_mul_f32 v[220:221], v[220:221], v[144:145]
	v_pk_mul_f32 v[230:231], v[214:215], v[244:245]
	v_pk_fma_f32 v[222:223], v[206:207], v[236:237], v[230:231] neg_lo:[0,0,1] neg_hi:[0,0,1]
	v_pk_mul_f32 v[230:231], v[206:207], v[244:245]
	v_pk_fma_f32 v[214:215], v[214:215], v[236:237], v[230:231]
	v_pk_mul_f32 v[174:175], v[216:217], v[246:247]
	v_pk_fma_f32 v[224:225], v[208:209], v[238:239], v[174:175] neg_lo:[0,0,1] neg_hi:[0,0,1]
	v_pk_mul_f32 v[174:175], v[208:209], v[246:247]
	v_pk_fma_f32 v[216:217], v[216:217], v[238:239], v[174:175]
	v_pk_mul_f32 v[230:231], v[218:219], v[248:249]
	v_pk_fma_f32 v[226:227], v[210:211], v[240:241], v[230:231] neg_lo:[0,0,1] neg_hi:[0,0,1]
	v_pk_mul_f32 v[230:231], v[210:211], v[248:249]
	v_pk_fma_f32 v[218:219], v[218:219], v[240:241], v[230:231]
	v_pk_mul_f32 v[174:175], v[220:221], v[250:251]
	v_pk_fma_f32 v[228:229], v[212:213], v[242:243], v[174:175] neg_lo:[0,0,1] neg_hi:[0,0,1]
	v_pk_mul_f32 v[174:175], v[212:213], v[250:251]
	v_pk_fma_f32 v[220:221], v[220:221], v[242:243], v[174:175]
	v_cvt_pk_bf16_f32 v222, v222, v223
	v_cvt_pk_bf16_f32 v223, v224, v225
	v_cvt_pk_bf16_f32 v224, v226, v227
	v_cvt_pk_bf16_f32 v225, v228, v229
	v_cvt_pk_bf16_f32 v214, v214, v215
	v_cvt_pk_bf16_f32 v215, v216, v217
	v_cvt_pk_bf16_f32 v216, v218, v219
	v_cvt_pk_bf16_f32 v217, v220, v221
	v_permlane16_swap_b32_e32 v222, v224
	v_permlane16_swap_b32_e32 v223, v225
	v_permlane16_swap_b32_e32 v214, v216
	v_permlane16_swap_b32_e32 v215, v217
	global_store_dwordx4 v[172:173], v[222:225], off
	global_store_dwordx4 v[172:173], v[214:217], off offset:64
	v_pk_mul_f32 v[174:175], v[110:111], v[110:111]
	v_pk_fma_f32 v[174:175], v[112:113], v[112:113], v[174:175]
	v_lshl_add_u64 v[172:173], v[172:173], 0, s[2:3]
	v_pk_fma_f32 v[174:175], v[102:103], v[102:103], v[174:175]
	v_pk_fma_f32 v[174:175], v[104:105], v[104:105], v[174:175]
	v_pk_fma_f32 v[174:175], v[106:107], v[106:107], v[174:175]
	v_pk_fma_f32 v[174:175], v[108:109], v[108:109], v[174:175]
	v_pk_fma_f32 v[174:175], v[98:99], v[98:99], v[174:175]
	v_pk_fma_f32 v[174:175], v[100:101], v[100:101], v[174:175]
	v_add_f32_e32 v174, v174, v175
	v_mov_b32_e32 v175, v174
	v_add_u32_e32 v166, 16, v160
	v_lshrrev_b32_e32 v166, 6, v166
	v_permlane16_swap_b32_e32 v175, v174
	v_add_f32_e32 v174, v174, v175
	v_mov_b32_e32 v175, v174
	v_cvt_f32_i32_e32 v166, v166
	v_mul_f32_e32 v166, s8, v166
	v_permlane32_swap_b32_e32 v175, v174
	v_add_f32_e32 v174, v174, v175
	v_fmamk_f32 v174, v174, 0x3c800000, v161
	v_rsq_f32_e32 v170, v174
	v_add_u32_e32 v168, 16, v160
	v_and_b32_e32 v168, 63, v168
	v_cvt_f32_i32_e32 v168, v168
	v_mul_f32_e32 v168, s8, v168
	v_pk_mul_f32 v[236:237], v[146:147], v[166:167] op_sel_hi:[1,0]
	v_pk_mul_f32 v[236:237], v[236:237], v[162:163]
	v_sin_f32_e32 v244, v236
	v_pk_mul_f32 v[238:239], v[148:149], v[166:167] op_sel_hi:[1,0]
	v_sin_f32_e32 v245, v237
	v_pk_mul_f32 v[238:239], v[238:239], v[162:163]
	v_sin_f32_e32 v246, v238
	v_pk_mul_f32 v[240:241], v[146:147], v[168:169] op_sel_hi:[1,0]
	v_sin_f32_e32 v247, v239
	v_pk_mul_f32 v[240:241], v[240:241], v[162:163]
	v_sin_f32_e32 v248, v240
	v_pk_mul_f32 v[242:243], v[148:149], v[168:169] op_sel_hi:[1,0]
	v_sin_f32_e32 v249, v241
	v_pk_mul_f32 v[242:243], v[242:243], v[162:163]
	v_sin_f32_e32 v250, v242
	v_pk_mul_f32 v[244:245], v[244:245], v[164:165]
	v_sin_f32_e32 v251, v243
	v_pk_mul_f32 v[246:247], v[246:247], v[164:165]
	v_cos_f32_e32 v236, v236
	v_pk_mul_f32 v[248:249], v[248:249], v[164:165]
	v_cos_f32_e32 v237, v237
	v_pk_mul_f32 v[250:251], v[250:251], v[164:165]
	v_cos_f32_e32 v238, v238
	v_pk_mul_f32 v[236:237], v[236:237], v[164:165]
	v_cos_f32_e32 v239, v239
	v_pk_mul_f32 v[206:207], v[110:111], v[170:171] op_sel_hi:[1,0]
	v_cos_f32_e32 v240, v240
	v_pk_mul_f32 v[238:239], v[238:239], v[164:165]
	v_cos_f32_e32 v241, v241
	v_pk_mul_f32 v[206:207], v[206:207], v[130:131]
	v_cos_f32_e32 v242, v242
	v_pk_mul_f32 v[240:241], v[240:241], v[164:165]
	v_cos_f32_e32 v243, v243
	v_pk_mul_f32 v[208:209], v[112:113], v[170:171] op_sel_hi:[1,0]
	v_pk_mul_f32 v[242:243], v[242:243], v[164:165]
	v_pk_mul_f32 v[208:209], v[208:209], v[132:133]
	v_pk_mul_f32 v[214:215], v[106:107], v[170:171] op_sel_hi:[1,0]
	v_pk_mul_f32 v[214:215], v[214:215], v[138:139]
	v_pk_mul_f32 v[216:217], v[108:109], v[170:171] op_sel_hi:[1,0]
	v_pk_mul_f32 v[216:217], v[216:217], v[140:141]
	v_pk_mul_f32 v[210:211], v[102:103], v[170:171] op_sel_hi:[1,0]
	v_pk_mul_f32 v[210:211], v[210:211], v[134:135]
	v_pk_mul_f32 v[212:213], v[104:105], v[170:171] op_sel_hi:[1,0]
	v_pk_mul_f32 v[212:213], v[212:213], v[136:137]
	v_pk_mul_f32 v[218:219], v[98:99], v[170:171] op_sel_hi:[1,0]
	v_pk_mul_f32 v[218:219], v[218:219], v[142:143]
	v_pk_mul_f32 v[220:221], v[100:101], v[170:171] op_sel_hi:[1,0]
	v_pk_mul_f32 v[220:221], v[220:221], v[144:145]
	v_pk_mul_f32 v[230:231], v[214:215], v[244:245]
	v_pk_fma_f32 v[222:223], v[206:207], v[236:237], v[230:231] neg_lo:[0,0,1] neg_hi:[0,0,1]
	v_pk_mul_f32 v[230:231], v[206:207], v[244:245]
	v_pk_fma_f32 v[214:215], v[214:215], v[236:237], v[230:231]
	v_pk_mul_f32 v[174:175], v[216:217], v[246:247]
	v_pk_fma_f32 v[224:225], v[208:209], v[238:239], v[174:175] neg_lo:[0,0,1] neg_hi:[0,0,1]
	v_pk_mul_f32 v[174:175], v[208:209], v[246:247]
	v_pk_fma_f32 v[216:217], v[216:217], v[238:239], v[174:175]
	v_pk_mul_f32 v[230:231], v[218:219], v[248:249]
	v_pk_fma_f32 v[226:227], v[210:211], v[240:241], v[230:231] neg_lo:[0,0,1] neg_hi:[0,0,1]
	v_pk_mul_f32 v[230:231], v[210:211], v[248:249]
	v_pk_fma_f32 v[218:219], v[218:219], v[240:241], v[230:231]
	v_pk_mul_f32 v[174:175], v[220:221], v[250:251]
	v_pk_fma_f32 v[228:229], v[212:213], v[242:243], v[174:175] neg_lo:[0,0,1] neg_hi:[0,0,1]
	v_pk_mul_f32 v[174:175], v[212:213], v[250:251]
	v_pk_fma_f32 v[220:221], v[220:221], v[242:243], v[174:175]
	v_cvt_pk_bf16_f32 v222, v222, v223
	v_cvt_pk_bf16_f32 v223, v224, v225
	v_cvt_pk_bf16_f32 v224, v226, v227
	v_cvt_pk_bf16_f32 v225, v228, v229
	v_cvt_pk_bf16_f32 v214, v214, v215
	v_cvt_pk_bf16_f32 v215, v216, v217
	v_cvt_pk_bf16_f32 v216, v218, v219
	v_cvt_pk_bf16_f32 v217, v220, v221
	v_permlane16_swap_b32_e32 v222, v224
	v_permlane16_swap_b32_e32 v223, v225
	v_permlane16_swap_b32_e32 v214, v216
	v_permlane16_swap_b32_e32 v215, v217
	global_store_dwordx4 v[172:173], v[222:225], off
	global_store_dwordx4 v[172:173], v[214:217], off offset:64
	v_pk_mul_f32 v[174:175], v[94:95], v[94:95]
	v_pk_fma_f32 v[174:175], v[96:97], v[96:97], v[174:175]
	v_lshl_add_u64 v[172:173], v[172:173], 0, s[2:3]
	v_pk_fma_f32 v[174:175], v[86:87], v[86:87], v[174:175]
	v_pk_fma_f32 v[174:175], v[88:89], v[88:89], v[174:175]
	v_pk_fma_f32 v[174:175], v[90:91], v[90:91], v[174:175]
	v_pk_fma_f32 v[174:175], v[92:93], v[92:93], v[174:175]
	v_pk_fma_f32 v[174:175], v[82:83], v[82:83], v[174:175]
	v_pk_fma_f32 v[174:175], v[84:85], v[84:85], v[174:175]
	v_add_f32_e32 v174, v174, v175
	v_mov_b32_e32 v175, v174
	v_add_u32_e32 v166, 32, v160
	v_lshrrev_b32_e32 v166, 6, v166
	v_permlane16_swap_b32_e32 v175, v174
	v_add_f32_e32 v174, v174, v175
	v_mov_b32_e32 v175, v174
	v_cvt_f32_i32_e32 v166, v166
	v_mul_f32_e32 v166, s8, v166
	v_permlane32_swap_b32_e32 v175, v174
	v_add_f32_e32 v174, v174, v175
	v_fmamk_f32 v174, v174, 0x3c800000, v161
	v_rsq_f32_e32 v170, v174
	v_add_u32_e32 v168, 32, v160
	v_and_b32_e32 v168, 63, v168
	v_cvt_f32_i32_e32 v168, v168
	v_mul_f32_e32 v168, s8, v168
	v_pk_mul_f32 v[236:237], v[146:147], v[166:167] op_sel_hi:[1,0]
	v_pk_mul_f32 v[236:237], v[236:237], v[162:163]
	v_sin_f32_e32 v244, v236
	v_pk_mul_f32 v[238:239], v[148:149], v[166:167] op_sel_hi:[1,0]
	v_sin_f32_e32 v245, v237
	v_pk_mul_f32 v[238:239], v[238:239], v[162:163]
	v_sin_f32_e32 v246, v238
	v_pk_mul_f32 v[240:241], v[146:147], v[168:169] op_sel_hi:[1,0]
	v_sin_f32_e32 v247, v239
	v_pk_mul_f32 v[240:241], v[240:241], v[162:163]
	v_sin_f32_e32 v248, v240
	v_pk_mul_f32 v[242:243], v[148:149], v[168:169] op_sel_hi:[1,0]
	v_sin_f32_e32 v249, v241
	v_pk_mul_f32 v[242:243], v[242:243], v[162:163]
	v_sin_f32_e32 v250, v242
	v_pk_mul_f32 v[244:245], v[244:245], v[164:165]
	v_sin_f32_e32 v251, v243
	v_pk_mul_f32 v[246:247], v[246:247], v[164:165]
	v_cos_f32_e32 v236, v236
	v_pk_mul_f32 v[248:249], v[248:249], v[164:165]
	v_cos_f32_e32 v237, v237
	v_pk_mul_f32 v[250:251], v[250:251], v[164:165]
	v_cos_f32_e32 v238, v238
	v_pk_mul_f32 v[236:237], v[236:237], v[164:165]
	v_cos_f32_e32 v239, v239
	v_pk_mul_f32 v[206:207], v[94:95], v[170:171] op_sel_hi:[1,0]
	v_cos_f32_e32 v240, v240
	v_pk_mul_f32 v[238:239], v[238:239], v[164:165]
	v_cos_f32_e32 v241, v241
	v_pk_mul_f32 v[206:207], v[206:207], v[130:131]
	v_cos_f32_e32 v242, v242
	v_pk_mul_f32 v[240:241], v[240:241], v[164:165]
	v_cos_f32_e32 v243, v243
	v_pk_mul_f32 v[208:209], v[96:97], v[170:171] op_sel_hi:[1,0]
	v_pk_mul_f32 v[242:243], v[242:243], v[164:165]
	v_pk_mul_f32 v[208:209], v[208:209], v[132:133]
	v_pk_mul_f32 v[214:215], v[90:91], v[170:171] op_sel_hi:[1,0]
	v_pk_mul_f32 v[214:215], v[214:215], v[138:139]
	v_pk_mul_f32 v[216:217], v[92:93], v[170:171] op_sel_hi:[1,0]
	v_pk_mul_f32 v[216:217], v[216:217], v[140:141]
	v_pk_mul_f32 v[210:211], v[86:87], v[170:171] op_sel_hi:[1,0]
	v_pk_mul_f32 v[210:211], v[210:211], v[134:135]
	v_pk_mul_f32 v[212:213], v[88:89], v[170:171] op_sel_hi:[1,0]
	v_pk_mul_f32 v[212:213], v[212:213], v[136:137]
	v_pk_mul_f32 v[218:219], v[82:83], v[170:171] op_sel_hi:[1,0]
	v_pk_mul_f32 v[218:219], v[218:219], v[142:143]
	v_pk_mul_f32 v[220:221], v[84:85], v[170:171] op_sel_hi:[1,0]
	v_pk_mul_f32 v[220:221], v[220:221], v[144:145]
	v_pk_mul_f32 v[230:231], v[214:215], v[244:245]
	v_pk_fma_f32 v[222:223], v[206:207], v[236:237], v[230:231] neg_lo:[0,0,1] neg_hi:[0,0,1]
	v_pk_mul_f32 v[230:231], v[206:207], v[244:245]
	v_pk_fma_f32 v[214:215], v[214:215], v[236:237], v[230:231]
	v_pk_mul_f32 v[174:175], v[216:217], v[246:247]
	v_pk_fma_f32 v[224:225], v[208:209], v[238:239], v[174:175] neg_lo:[0,0,1] neg_hi:[0,0,1]
	v_pk_mul_f32 v[174:175], v[208:209], v[246:247]
	v_pk_fma_f32 v[216:217], v[216:217], v[238:239], v[174:175]
	v_pk_mul_f32 v[230:231], v[218:219], v[248:249]
	v_pk_fma_f32 v[226:227], v[210:211], v[240:241], v[230:231] neg_lo:[0,0,1] neg_hi:[0,0,1]
	v_pk_mul_f32 v[230:231], v[210:211], v[248:249]
	v_pk_fma_f32 v[218:219], v[218:219], v[240:241], v[230:231]
	v_pk_mul_f32 v[174:175], v[220:221], v[250:251]
	v_pk_fma_f32 v[228:229], v[212:213], v[242:243], v[174:175] neg_lo:[0,0,1] neg_hi:[0,0,1]
	v_pk_mul_f32 v[174:175], v[212:213], v[250:251]
	v_pk_fma_f32 v[220:221], v[220:221], v[242:243], v[174:175]
	v_cvt_pk_bf16_f32 v222, v222, v223
	v_cvt_pk_bf16_f32 v223, v224, v225
	v_cvt_pk_bf16_f32 v224, v226, v227
	v_cvt_pk_bf16_f32 v225, v228, v229
	v_cvt_pk_bf16_f32 v214, v214, v215
	v_cvt_pk_bf16_f32 v215, v216, v217
	v_cvt_pk_bf16_f32 v216, v218, v219
	v_cvt_pk_bf16_f32 v217, v220, v221
	v_permlane16_swap_b32_e32 v222, v224
	v_permlane16_swap_b32_e32 v223, v225
	v_permlane16_swap_b32_e32 v214, v216
	v_permlane16_swap_b32_e32 v215, v217
	global_store_dwordx4 v[172:173], v[222:225], off
	global_store_dwordx4 v[172:173], v[214:217], off offset:64
	v_pk_mul_f32 v[174:175], v[78:79], v[78:79]
	v_pk_fma_f32 v[174:175], v[80:81], v[80:81], v[174:175]
	v_lshl_add_u64 v[172:173], v[172:173], 0, s[2:3]
	v_pk_fma_f32 v[174:175], v[70:71], v[70:71], v[174:175]
	v_pk_fma_f32 v[174:175], v[72:73], v[72:73], v[174:175]
	v_pk_fma_f32 v[174:175], v[74:75], v[74:75], v[174:175]
	v_pk_fma_f32 v[174:175], v[76:77], v[76:77], v[174:175]
	v_pk_fma_f32 v[174:175], v[66:67], v[66:67], v[174:175]
	v_pk_fma_f32 v[174:175], v[68:69], v[68:69], v[174:175]
	v_add_f32_e32 v174, v174, v175
	v_mov_b32_e32 v175, v174
	v_add_u32_e32 v166, 48, v160
	v_lshrrev_b32_e32 v166, 6, v166
	v_permlane16_swap_b32_e32 v175, v174
	v_add_f32_e32 v174, v174, v175
	v_mov_b32_e32 v175, v174
	v_cvt_f32_i32_e32 v166, v166
	v_mul_f32_e32 v166, s8, v166
	v_permlane32_swap_b32_e32 v175, v174
	v_add_f32_e32 v174, v174, v175
	v_fmamk_f32 v174, v174, 0x3c800000, v161
	v_rsq_f32_e32 v170, v174
	v_add_u32_e32 v168, 48, v160
	v_and_b32_e32 v168, 63, v168
	v_cvt_f32_i32_e32 v168, v168
	v_mul_f32_e32 v168, s8, v168
	v_pk_mul_f32 v[236:237], v[146:147], v[166:167] op_sel_hi:[1,0]
	v_pk_mul_f32 v[236:237], v[236:237], v[162:163]
	v_sin_f32_e32 v244, v236
	v_pk_mul_f32 v[238:239], v[148:149], v[166:167] op_sel_hi:[1,0]
	v_sin_f32_e32 v245, v237
	v_pk_mul_f32 v[238:239], v[238:239], v[162:163]
	v_sin_f32_e32 v246, v238
	v_pk_mul_f32 v[240:241], v[146:147], v[168:169] op_sel_hi:[1,0]
	v_sin_f32_e32 v247, v239
	v_pk_mul_f32 v[240:241], v[240:241], v[162:163]
	v_sin_f32_e32 v248, v240
	v_pk_mul_f32 v[242:243], v[148:149], v[168:169] op_sel_hi:[1,0]
	v_sin_f32_e32 v249, v241
	v_pk_mul_f32 v[242:243], v[242:243], v[162:163]
	v_sin_f32_e32 v250, v242
	v_pk_mul_f32 v[244:245], v[244:245], v[164:165]
	v_sin_f32_e32 v251, v243
	v_pk_mul_f32 v[246:247], v[246:247], v[164:165]
	v_cos_f32_e32 v236, v236
	v_pk_mul_f32 v[248:249], v[248:249], v[164:165]
	v_cos_f32_e32 v237, v237
	v_pk_mul_f32 v[250:251], v[250:251], v[164:165]
	v_cos_f32_e32 v238, v238
	v_pk_mul_f32 v[236:237], v[236:237], v[164:165]
	v_cos_f32_e32 v239, v239
	v_pk_mul_f32 v[206:207], v[78:79], v[170:171] op_sel_hi:[1,0]
	v_cos_f32_e32 v240, v240
	v_pk_mul_f32 v[238:239], v[238:239], v[164:165]
	v_cos_f32_e32 v241, v241
	v_pk_mul_f32 v[206:207], v[206:207], v[130:131]
	v_cos_f32_e32 v242, v242
	v_pk_mul_f32 v[240:241], v[240:241], v[164:165]
	v_cos_f32_e32 v243, v243
	v_pk_mul_f32 v[208:209], v[80:81], v[170:171] op_sel_hi:[1,0]
	v_pk_mul_f32 v[242:243], v[242:243], v[164:165]
	v_pk_mul_f32 v[208:209], v[208:209], v[132:133]
	v_pk_mul_f32 v[214:215], v[74:75], v[170:171] op_sel_hi:[1,0]
	v_pk_mul_f32 v[214:215], v[214:215], v[138:139]
	v_pk_mul_f32 v[216:217], v[76:77], v[170:171] op_sel_hi:[1,0]
	v_pk_mul_f32 v[216:217], v[216:217], v[140:141]
	v_pk_mul_f32 v[210:211], v[70:71], v[170:171] op_sel_hi:[1,0]
	v_pk_mul_f32 v[210:211], v[210:211], v[134:135]
	v_pk_mul_f32 v[212:213], v[72:73], v[170:171] op_sel_hi:[1,0]
	v_pk_mul_f32 v[212:213], v[212:213], v[136:137]
	v_pk_mul_f32 v[218:219], v[66:67], v[170:171] op_sel_hi:[1,0]
	v_pk_mul_f32 v[218:219], v[218:219], v[142:143]
	v_pk_mul_f32 v[220:221], v[68:69], v[170:171] op_sel_hi:[1,0]
	v_pk_mul_f32 v[220:221], v[220:221], v[144:145]
	v_pk_mul_f32 v[230:231], v[214:215], v[244:245]
	v_pk_fma_f32 v[222:223], v[206:207], v[236:237], v[230:231] neg_lo:[0,0,1] neg_hi:[0,0,1]
	v_pk_mul_f32 v[230:231], v[206:207], v[244:245]
	v_pk_fma_f32 v[214:215], v[214:215], v[236:237], v[230:231]
	v_pk_mul_f32 v[174:175], v[216:217], v[246:247]
	v_pk_fma_f32 v[224:225], v[208:209], v[238:239], v[174:175] neg_lo:[0,0,1] neg_hi:[0,0,1]
	v_pk_mul_f32 v[174:175], v[208:209], v[246:247]
	v_pk_fma_f32 v[216:217], v[216:217], v[238:239], v[174:175]
	v_pk_mul_f32 v[230:231], v[218:219], v[248:249]
	v_pk_fma_f32 v[226:227], v[210:211], v[240:241], v[230:231] neg_lo:[0,0,1] neg_hi:[0,0,1]
	v_pk_mul_f32 v[230:231], v[210:211], v[248:249]
	v_pk_fma_f32 v[218:219], v[218:219], v[240:241], v[230:231]
	v_pk_mul_f32 v[174:175], v[220:221], v[250:251]
	v_pk_fma_f32 v[228:229], v[212:213], v[242:243], v[174:175] neg_lo:[0,0,1] neg_hi:[0,0,1]
	v_pk_mul_f32 v[174:175], v[212:213], v[250:251]
	v_pk_fma_f32 v[220:221], v[220:221], v[242:243], v[174:175]
	v_cvt_pk_bf16_f32 v222, v222, v223
	v_cvt_pk_bf16_f32 v223, v224, v225
	v_cvt_pk_bf16_f32 v224, v226, v227
	v_cvt_pk_bf16_f32 v225, v228, v229
	v_cvt_pk_bf16_f32 v214, v214, v215
	v_cvt_pk_bf16_f32 v215, v216, v217
	v_cvt_pk_bf16_f32 v216, v218, v219
	v_cvt_pk_bf16_f32 v217, v220, v221
	v_permlane16_swap_b32_e32 v222, v224
	v_permlane16_swap_b32_e32 v223, v225
	v_permlane16_swap_b32_e32 v214, v216
	v_permlane16_swap_b32_e32 v215, v217
	global_store_dwordx4 v[172:173], v[222:225], off
	global_store_dwordx4 v[172:173], v[214:217], off offset:64
	v_pk_mul_f32 v[174:175], v[62:63], v[62:63]
	v_pk_fma_f32 v[174:175], v[64:65], v[64:65], v[174:175]
	v_lshl_add_u64 v[172:173], v[172:173], 0, s[28:29]
	v_pk_fma_f32 v[174:175], v[54:55], v[54:55], v[174:175]
	v_pk_fma_f32 v[174:175], v[56:57], v[56:57], v[174:175]
	v_pk_fma_f32 v[174:175], v[58:59], v[58:59], v[174:175]
	v_pk_fma_f32 v[174:175], v[60:61], v[60:61], v[174:175]
	v_pk_fma_f32 v[174:175], v[50:51], v[50:51], v[174:175]
	v_pk_fma_f32 v[174:175], v[52:53], v[52:53], v[174:175]
	v_add_f32_e32 v174, v174, v175
	v_mov_b32_e32 v175, v174
	v_add_u32_e32 v166, 128, v160
	v_lshrrev_b32_e32 v166, 6, v166
	v_permlane16_swap_b32_e32 v175, v174
	v_add_f32_e32 v174, v174, v175
	v_mov_b32_e32 v175, v174
	v_cvt_f32_i32_e32 v166, v166
	v_mul_f32_e32 v166, s8, v166
	v_permlane32_swap_b32_e32 v175, v174
	v_add_f32_e32 v174, v174, v175
	v_fmamk_f32 v174, v174, 0x3c800000, v161
	v_rsq_f32_e32 v170, v174
	v_add_u32_e32 v168, 128, v160
	v_and_b32_e32 v168, 63, v168
	v_cvt_f32_i32_e32 v168, v168
	v_mul_f32_e32 v168, s8, v168
	v_pk_mul_f32 v[236:237], v[146:147], v[166:167] op_sel_hi:[1,0]
	v_pk_mul_f32 v[236:237], v[236:237], v[162:163]
	v_sin_f32_e32 v244, v236
	v_pk_mul_f32 v[238:239], v[148:149], v[166:167] op_sel_hi:[1,0]
	v_sin_f32_e32 v245, v237
	v_pk_mul_f32 v[238:239], v[238:239], v[162:163]
	v_sin_f32_e32 v246, v238
	v_pk_mul_f32 v[240:241], v[146:147], v[168:169] op_sel_hi:[1,0]
	v_sin_f32_e32 v247, v239
	v_pk_mul_f32 v[240:241], v[240:241], v[162:163]
	v_sin_f32_e32 v248, v240
	v_pk_mul_f32 v[242:243], v[148:149], v[168:169] op_sel_hi:[1,0]
	v_sin_f32_e32 v249, v241
	v_pk_mul_f32 v[242:243], v[242:243], v[162:163]
	v_sin_f32_e32 v250, v242
	v_pk_mul_f32 v[244:245], v[244:245], v[164:165]
	v_sin_f32_e32 v251, v243
	v_pk_mul_f32 v[246:247], v[246:247], v[164:165]
	v_cos_f32_e32 v236, v236
	v_pk_mul_f32 v[248:249], v[248:249], v[164:165]
	v_cos_f32_e32 v237, v237
	v_pk_mul_f32 v[250:251], v[250:251], v[164:165]
	v_cos_f32_e32 v238, v238
	v_pk_mul_f32 v[236:237], v[236:237], v[164:165]
	v_cos_f32_e32 v239, v239
	v_pk_mul_f32 v[206:207], v[62:63], v[170:171] op_sel_hi:[1,0]
	v_cos_f32_e32 v240, v240
	v_pk_mul_f32 v[238:239], v[238:239], v[164:165]
	v_cos_f32_e32 v241, v241
	v_pk_mul_f32 v[206:207], v[206:207], v[130:131]
	v_cos_f32_e32 v242, v242
	v_pk_mul_f32 v[240:241], v[240:241], v[164:165]
	v_cos_f32_e32 v243, v243
	v_pk_mul_f32 v[208:209], v[64:65], v[170:171] op_sel_hi:[1,0]
	v_pk_mul_f32 v[242:243], v[242:243], v[164:165]
	v_pk_mul_f32 v[208:209], v[208:209], v[132:133]
	v_pk_mul_f32 v[214:215], v[58:59], v[170:171] op_sel_hi:[1,0]
	v_pk_mul_f32 v[214:215], v[214:215], v[138:139]
	v_pk_mul_f32 v[216:217], v[60:61], v[170:171] op_sel_hi:[1,0]
	v_pk_mul_f32 v[216:217], v[216:217], v[140:141]
	v_pk_mul_f32 v[210:211], v[54:55], v[170:171] op_sel_hi:[1,0]
	v_pk_mul_f32 v[210:211], v[210:211], v[134:135]
	v_pk_mul_f32 v[212:213], v[56:57], v[170:171] op_sel_hi:[1,0]
	v_pk_mul_f32 v[212:213], v[212:213], v[136:137]
	v_pk_mul_f32 v[218:219], v[50:51], v[170:171] op_sel_hi:[1,0]
	v_pk_mul_f32 v[218:219], v[218:219], v[142:143]
	v_pk_mul_f32 v[220:221], v[52:53], v[170:171] op_sel_hi:[1,0]
	v_pk_mul_f32 v[220:221], v[220:221], v[144:145]
	v_pk_mul_f32 v[230:231], v[214:215], v[244:245]
	v_pk_fma_f32 v[222:223], v[206:207], v[236:237], v[230:231] neg_lo:[0,0,1] neg_hi:[0,0,1]
	v_pk_mul_f32 v[230:231], v[206:207], v[244:245]
	v_pk_fma_f32 v[214:215], v[214:215], v[236:237], v[230:231]
	v_pk_mul_f32 v[174:175], v[216:217], v[246:247]
	v_pk_fma_f32 v[224:225], v[208:209], v[238:239], v[174:175] neg_lo:[0,0,1] neg_hi:[0,0,1]
	v_pk_mul_f32 v[174:175], v[208:209], v[246:247]
	v_pk_fma_f32 v[216:217], v[216:217], v[238:239], v[174:175]
	v_pk_mul_f32 v[230:231], v[218:219], v[248:249]
	v_pk_fma_f32 v[226:227], v[210:211], v[240:241], v[230:231] neg_lo:[0,0,1] neg_hi:[0,0,1]
	v_pk_mul_f32 v[230:231], v[210:211], v[248:249]
	v_pk_fma_f32 v[218:219], v[218:219], v[240:241], v[230:231]
	v_pk_mul_f32 v[174:175], v[220:221], v[250:251]
	v_pk_fma_f32 v[228:229], v[212:213], v[242:243], v[174:175] neg_lo:[0,0,1] neg_hi:[0,0,1]
	v_pk_mul_f32 v[174:175], v[212:213], v[250:251]
	v_pk_fma_f32 v[220:221], v[220:221], v[242:243], v[174:175]
	v_cvt_pk_bf16_f32 v222, v222, v223
	v_cvt_pk_bf16_f32 v223, v224, v225
	v_cvt_pk_bf16_f32 v224, v226, v227
	v_cvt_pk_bf16_f32 v225, v228, v229
	v_cvt_pk_bf16_f32 v214, v214, v215
	v_cvt_pk_bf16_f32 v215, v216, v217
	v_cvt_pk_bf16_f32 v216, v218, v219
	v_cvt_pk_bf16_f32 v217, v220, v221
	v_permlane16_swap_b32_e32 v222, v224
	v_permlane16_swap_b32_e32 v223, v225
	v_permlane16_swap_b32_e32 v214, v216
	v_permlane16_swap_b32_e32 v215, v217
	global_store_dwordx4 v[172:173], v[222:225], off
	global_store_dwordx4 v[172:173], v[214:217], off offset:64
	v_pk_mul_f32 v[174:175], v[46:47], v[46:47]
	v_pk_fma_f32 v[174:175], v[48:49], v[48:49], v[174:175]
	v_lshl_add_u64 v[172:173], v[172:173], 0, s[2:3]
	v_pk_fma_f32 v[174:175], v[38:39], v[38:39], v[174:175]
	v_pk_fma_f32 v[174:175], v[40:41], v[40:41], v[174:175]
	v_pk_fma_f32 v[174:175], v[42:43], v[42:43], v[174:175]
	v_pk_fma_f32 v[174:175], v[44:45], v[44:45], v[174:175]
	v_pk_fma_f32 v[174:175], v[34:35], v[34:35], v[174:175]
	v_pk_fma_f32 v[174:175], v[36:37], v[36:37], v[174:175]
	v_add_f32_e32 v174, v174, v175
	v_mov_b32_e32 v175, v174
	v_add_u32_e32 v166, 144, v160
	v_lshrrev_b32_e32 v166, 6, v166
	v_permlane16_swap_b32_e32 v175, v174
	v_add_f32_e32 v174, v174, v175
	v_mov_b32_e32 v175, v174
	v_cvt_f32_i32_e32 v166, v166
	v_mul_f32_e32 v166, s8, v166
	v_permlane32_swap_b32_e32 v175, v174
	v_add_f32_e32 v174, v174, v175
	v_fmamk_f32 v174, v174, 0x3c800000, v161
	v_rsq_f32_e32 v170, v174
	v_add_u32_e32 v168, 144, v160
	v_and_b32_e32 v168, 63, v168
	v_cvt_f32_i32_e32 v168, v168
	v_mul_f32_e32 v168, s8, v168
	v_pk_mul_f32 v[236:237], v[146:147], v[166:167] op_sel_hi:[1,0]
	v_pk_mul_f32 v[236:237], v[236:237], v[162:163]
	v_sin_f32_e32 v244, v236
	v_pk_mul_f32 v[238:239], v[148:149], v[166:167] op_sel_hi:[1,0]
	v_sin_f32_e32 v245, v237
	v_pk_mul_f32 v[238:239], v[238:239], v[162:163]
	v_sin_f32_e32 v246, v238
	v_pk_mul_f32 v[240:241], v[146:147], v[168:169] op_sel_hi:[1,0]
	v_sin_f32_e32 v247, v239
	v_pk_mul_f32 v[240:241], v[240:241], v[162:163]
	v_sin_f32_e32 v248, v240
	v_pk_mul_f32 v[242:243], v[148:149], v[168:169] op_sel_hi:[1,0]
	v_sin_f32_e32 v249, v241
	v_pk_mul_f32 v[242:243], v[242:243], v[162:163]
	v_sin_f32_e32 v250, v242
	v_pk_mul_f32 v[244:245], v[244:245], v[164:165]
	v_sin_f32_e32 v251, v243
	v_pk_mul_f32 v[246:247], v[246:247], v[164:165]
	v_cos_f32_e32 v236, v236
	v_pk_mul_f32 v[248:249], v[248:249], v[164:165]
	v_cos_f32_e32 v237, v237
	v_pk_mul_f32 v[250:251], v[250:251], v[164:165]
	v_cos_f32_e32 v238, v238
	v_pk_mul_f32 v[236:237], v[236:237], v[164:165]
	v_cos_f32_e32 v239, v239
	v_pk_mul_f32 v[206:207], v[46:47], v[170:171] op_sel_hi:[1,0]
	v_cos_f32_e32 v240, v240
	v_pk_mul_f32 v[238:239], v[238:239], v[164:165]
	v_cos_f32_e32 v241, v241
	v_pk_mul_f32 v[206:207], v[206:207], v[130:131]
	v_cos_f32_e32 v242, v242
	v_pk_mul_f32 v[240:241], v[240:241], v[164:165]
	v_cos_f32_e32 v243, v243
	v_pk_mul_f32 v[208:209], v[48:49], v[170:171] op_sel_hi:[1,0]
	v_pk_mul_f32 v[242:243], v[242:243], v[164:165]
	v_pk_mul_f32 v[208:209], v[208:209], v[132:133]
	v_pk_mul_f32 v[214:215], v[42:43], v[170:171] op_sel_hi:[1,0]
	v_pk_mul_f32 v[214:215], v[214:215], v[138:139]
	v_pk_mul_f32 v[216:217], v[44:45], v[170:171] op_sel_hi:[1,0]
	v_pk_mul_f32 v[216:217], v[216:217], v[140:141]
	v_pk_mul_f32 v[210:211], v[38:39], v[170:171] op_sel_hi:[1,0]
	v_pk_mul_f32 v[210:211], v[210:211], v[134:135]
	v_pk_mul_f32 v[212:213], v[40:41], v[170:171] op_sel_hi:[1,0]
	v_pk_mul_f32 v[212:213], v[212:213], v[136:137]
	v_pk_mul_f32 v[218:219], v[34:35], v[170:171] op_sel_hi:[1,0]
	v_pk_mul_f32 v[218:219], v[218:219], v[142:143]
	v_pk_mul_f32 v[220:221], v[36:37], v[170:171] op_sel_hi:[1,0]
	v_pk_mul_f32 v[220:221], v[220:221], v[144:145]
	v_pk_mul_f32 v[230:231], v[214:215], v[244:245]
	v_pk_fma_f32 v[222:223], v[206:207], v[236:237], v[230:231] neg_lo:[0,0,1] neg_hi:[0,0,1]
	v_pk_mul_f32 v[230:231], v[206:207], v[244:245]
	v_pk_fma_f32 v[214:215], v[214:215], v[236:237], v[230:231]
	v_pk_mul_f32 v[174:175], v[216:217], v[246:247]
	v_pk_fma_f32 v[224:225], v[208:209], v[238:239], v[174:175] neg_lo:[0,0,1] neg_hi:[0,0,1]
	v_pk_mul_f32 v[174:175], v[208:209], v[246:247]
	v_pk_fma_f32 v[216:217], v[216:217], v[238:239], v[174:175]
	v_pk_mul_f32 v[230:231], v[218:219], v[248:249]
	v_pk_fma_f32 v[226:227], v[210:211], v[240:241], v[230:231] neg_lo:[0,0,1] neg_hi:[0,0,1]
	v_pk_mul_f32 v[230:231], v[210:211], v[248:249]
	v_pk_fma_f32 v[218:219], v[218:219], v[240:241], v[230:231]
	v_pk_mul_f32 v[174:175], v[220:221], v[250:251]
	v_pk_fma_f32 v[228:229], v[212:213], v[242:243], v[174:175] neg_lo:[0,0,1] neg_hi:[0,0,1]
	v_pk_mul_f32 v[174:175], v[212:213], v[250:251]
	v_pk_fma_f32 v[220:221], v[220:221], v[242:243], v[174:175]
	v_cvt_pk_bf16_f32 v222, v222, v223
	v_cvt_pk_bf16_f32 v223, v224, v225
	v_cvt_pk_bf16_f32 v224, v226, v227
	v_cvt_pk_bf16_f32 v225, v228, v229
	v_cvt_pk_bf16_f32 v214, v214, v215
	v_cvt_pk_bf16_f32 v215, v216, v217
	v_cvt_pk_bf16_f32 v216, v218, v219
	v_cvt_pk_bf16_f32 v217, v220, v221
	v_permlane16_swap_b32_e32 v222, v224
	v_permlane16_swap_b32_e32 v223, v225
	v_permlane16_swap_b32_e32 v214, v216
	v_permlane16_swap_b32_e32 v215, v217
	global_store_dwordx4 v[172:173], v[222:225], off
	global_store_dwordx4 v[172:173], v[214:217], off offset:64
	v_pk_mul_f32 v[174:175], v[30:31], v[30:31]
	v_pk_fma_f32 v[174:175], v[32:33], v[32:33], v[174:175]
	v_lshl_add_u64 v[172:173], v[172:173], 0, s[2:3]
	v_pk_fma_f32 v[174:175], v[22:23], v[22:23], v[174:175]
	v_pk_fma_f32 v[174:175], v[24:25], v[24:25], v[174:175]
	v_pk_fma_f32 v[174:175], v[26:27], v[26:27], v[174:175]
	v_pk_fma_f32 v[174:175], v[28:29], v[28:29], v[174:175]
	v_pk_fma_f32 v[174:175], v[18:19], v[18:19], v[174:175]
	v_pk_fma_f32 v[174:175], v[20:21], v[20:21], v[174:175]
	v_add_f32_e32 v174, v174, v175
	v_mov_b32_e32 v175, v174
	v_add_u32_e32 v166, 160, v160
	v_lshrrev_b32_e32 v166, 6, v166
	v_permlane16_swap_b32_e32 v175, v174
	v_add_f32_e32 v174, v174, v175
	v_mov_b32_e32 v175, v174
	v_cvt_f32_i32_e32 v166, v166
	v_mul_f32_e32 v166, s8, v166
	v_permlane32_swap_b32_e32 v175, v174
	v_add_f32_e32 v174, v174, v175
	v_fmamk_f32 v174, v174, 0x3c800000, v161
	v_rsq_f32_e32 v170, v174
	v_add_u32_e32 v168, 160, v160
	v_and_b32_e32 v168, 63, v168
	v_cvt_f32_i32_e32 v168, v168
	v_mul_f32_e32 v168, s8, v168
	v_pk_mul_f32 v[236:237], v[146:147], v[166:167] op_sel_hi:[1,0]
	v_pk_mul_f32 v[236:237], v[236:237], v[162:163]
	v_sin_f32_e32 v244, v236
	v_pk_mul_f32 v[238:239], v[148:149], v[166:167] op_sel_hi:[1,0]
	v_sin_f32_e32 v245, v237
	v_pk_mul_f32 v[238:239], v[238:239], v[162:163]
	v_sin_f32_e32 v246, v238
	v_pk_mul_f32 v[240:241], v[146:147], v[168:169] op_sel_hi:[1,0]
	v_sin_f32_e32 v247, v239
	v_pk_mul_f32 v[240:241], v[240:241], v[162:163]
	v_sin_f32_e32 v248, v240
	v_pk_mul_f32 v[242:243], v[148:149], v[168:169] op_sel_hi:[1,0]
	v_sin_f32_e32 v249, v241
	v_pk_mul_f32 v[242:243], v[242:243], v[162:163]
	v_sin_f32_e32 v250, v242
	v_pk_mul_f32 v[244:245], v[244:245], v[164:165]
	v_sin_f32_e32 v251, v243
	v_pk_mul_f32 v[246:247], v[246:247], v[164:165]
	v_cos_f32_e32 v236, v236
	v_pk_mul_f32 v[248:249], v[248:249], v[164:165]
	v_cos_f32_e32 v237, v237
	v_pk_mul_f32 v[250:251], v[250:251], v[164:165]
	v_cos_f32_e32 v238, v238
	v_pk_mul_f32 v[236:237], v[236:237], v[164:165]
	v_cos_f32_e32 v239, v239
	v_pk_mul_f32 v[206:207], v[30:31], v[170:171] op_sel_hi:[1,0]
	v_cos_f32_e32 v240, v240
	v_pk_mul_f32 v[238:239], v[238:239], v[164:165]
	v_cos_f32_e32 v241, v241
	v_pk_mul_f32 v[206:207], v[206:207], v[130:131]
	v_cos_f32_e32 v242, v242
	v_pk_mul_f32 v[240:241], v[240:241], v[164:165]
	v_cos_f32_e32 v243, v243
	v_pk_mul_f32 v[208:209], v[32:33], v[170:171] op_sel_hi:[1,0]
	v_pk_mul_f32 v[242:243], v[242:243], v[164:165]
	v_pk_mul_f32 v[208:209], v[208:209], v[132:133]
	v_pk_mul_f32 v[214:215], v[26:27], v[170:171] op_sel_hi:[1,0]
	v_pk_mul_f32 v[214:215], v[214:215], v[138:139]
	v_pk_mul_f32 v[216:217], v[28:29], v[170:171] op_sel_hi:[1,0]
	v_pk_mul_f32 v[216:217], v[216:217], v[140:141]
	v_pk_mul_f32 v[210:211], v[22:23], v[170:171] op_sel_hi:[1,0]
	v_pk_mul_f32 v[210:211], v[210:211], v[134:135]
	v_pk_mul_f32 v[212:213], v[24:25], v[170:171] op_sel_hi:[1,0]
	v_pk_mul_f32 v[212:213], v[212:213], v[136:137]
	v_pk_mul_f32 v[218:219], v[18:19], v[170:171] op_sel_hi:[1,0]
	v_pk_mul_f32 v[218:219], v[218:219], v[142:143]
	v_pk_mul_f32 v[220:221], v[20:21], v[170:171] op_sel_hi:[1,0]
	v_pk_mul_f32 v[220:221], v[220:221], v[144:145]
	v_pk_mul_f32 v[230:231], v[214:215], v[244:245]
	v_pk_fma_f32 v[222:223], v[206:207], v[236:237], v[230:231] neg_lo:[0,0,1] neg_hi:[0,0,1]
	v_pk_mul_f32 v[230:231], v[206:207], v[244:245]
	v_pk_fma_f32 v[214:215], v[214:215], v[236:237], v[230:231]
	v_pk_mul_f32 v[174:175], v[216:217], v[246:247]
	v_pk_fma_f32 v[224:225], v[208:209], v[238:239], v[174:175] neg_lo:[0,0,1] neg_hi:[0,0,1]
	v_pk_mul_f32 v[174:175], v[208:209], v[246:247]
	v_pk_fma_f32 v[216:217], v[216:217], v[238:239], v[174:175]
	v_pk_mul_f32 v[230:231], v[218:219], v[248:249]
	v_pk_fma_f32 v[226:227], v[210:211], v[240:241], v[230:231] neg_lo:[0,0,1] neg_hi:[0,0,1]
	v_pk_mul_f32 v[230:231], v[210:211], v[248:249]
	v_pk_fma_f32 v[218:219], v[218:219], v[240:241], v[230:231]
	v_pk_mul_f32 v[174:175], v[220:221], v[250:251]
	v_pk_fma_f32 v[228:229], v[212:213], v[242:243], v[174:175] neg_lo:[0,0,1] neg_hi:[0,0,1]
	v_pk_mul_f32 v[174:175], v[212:213], v[250:251]
	v_pk_fma_f32 v[220:221], v[220:221], v[242:243], v[174:175]
	v_cvt_pk_bf16_f32 v222, v222, v223
	v_cvt_pk_bf16_f32 v223, v224, v225
	v_cvt_pk_bf16_f32 v224, v226, v227
	v_cvt_pk_bf16_f32 v225, v228, v229
	v_cvt_pk_bf16_f32 v214, v214, v215
	v_cvt_pk_bf16_f32 v215, v216, v217
	v_cvt_pk_bf16_f32 v216, v218, v219
	v_cvt_pk_bf16_f32 v217, v220, v221
	v_permlane16_swap_b32_e32 v222, v224
	v_permlane16_swap_b32_e32 v223, v225
	v_permlane16_swap_b32_e32 v214, v216
	v_permlane16_swap_b32_e32 v215, v217
	global_store_dwordx4 v[172:173], v[222:225], off
	global_store_dwordx4 v[172:173], v[214:217], off offset:64
	v_pk_mul_f32 v[174:175], v[14:15], v[14:15]
	v_pk_fma_f32 v[174:175], v[16:17], v[16:17], v[174:175]
	v_lshl_add_u64 v[172:173], v[172:173], 0, s[2:3]
	v_pk_fma_f32 v[174:175], v[6:7], v[6:7], v[174:175]
	v_pk_fma_f32 v[174:175], v[8:9], v[8:9], v[174:175]
	v_pk_fma_f32 v[174:175], v[10:11], v[10:11], v[174:175]
	v_pk_fma_f32 v[174:175], v[12:13], v[12:13], v[174:175]
	v_pk_fma_f32 v[174:175], v[2:3], v[2:3], v[174:175]
	v_pk_fma_f32 v[174:175], v[4:5], v[4:5], v[174:175]
	v_add_f32_e32 v174, v174, v175
	v_mov_b32_e32 v175, v174
	v_add_u32_e32 v166, 176, v160
	v_lshrrev_b32_e32 v166, 6, v166
	v_permlane16_swap_b32_e32 v175, v174
	v_add_f32_e32 v174, v174, v175
	v_mov_b32_e32 v175, v174
	v_cvt_f32_i32_e32 v166, v166
	v_mul_f32_e32 v166, s8, v166
	v_permlane32_swap_b32_e32 v175, v174
	v_add_f32_e32 v174, v174, v175
	v_fmamk_f32 v174, v174, 0x3c800000, v161
	v_rsq_f32_e32 v170, v174
	v_add_u32_e32 v168, 176, v160
	v_and_b32_e32 v168, 63, v168
	v_cvt_f32_i32_e32 v168, v168
	v_mul_f32_e32 v168, s8, v168
	v_pk_mul_f32 v[236:237], v[146:147], v[166:167] op_sel_hi:[1,0]
	v_pk_mul_f32 v[236:237], v[236:237], v[162:163]
	v_sin_f32_e32 v244, v236
	v_pk_mul_f32 v[238:239], v[148:149], v[166:167] op_sel_hi:[1,0]
	v_sin_f32_e32 v245, v237
	v_pk_mul_f32 v[238:239], v[238:239], v[162:163]
	v_sin_f32_e32 v246, v238
	v_pk_mul_f32 v[240:241], v[146:147], v[168:169] op_sel_hi:[1,0]
	v_sin_f32_e32 v247, v239
	v_pk_mul_f32 v[240:241], v[240:241], v[162:163]
	v_sin_f32_e32 v248, v240
	v_pk_mul_f32 v[242:243], v[148:149], v[168:169] op_sel_hi:[1,0]
	v_sin_f32_e32 v249, v241
	v_pk_mul_f32 v[242:243], v[242:243], v[162:163]
	v_sin_f32_e32 v250, v242
	v_pk_mul_f32 v[244:245], v[244:245], v[164:165]
	v_sin_f32_e32 v251, v243
	v_pk_mul_f32 v[246:247], v[246:247], v[164:165]
	v_cos_f32_e32 v236, v236
	v_pk_mul_f32 v[248:249], v[248:249], v[164:165]
	v_cos_f32_e32 v237, v237
	v_pk_mul_f32 v[250:251], v[250:251], v[164:165]
	v_cos_f32_e32 v238, v238
	v_pk_mul_f32 v[236:237], v[236:237], v[164:165]
	v_cos_f32_e32 v239, v239
	v_pk_mul_f32 v[206:207], v[14:15], v[170:171] op_sel_hi:[1,0]
	v_cos_f32_e32 v240, v240
	v_pk_mul_f32 v[238:239], v[238:239], v[164:165]
	v_cos_f32_e32 v241, v241
	v_pk_mul_f32 v[206:207], v[206:207], v[130:131]
	v_cos_f32_e32 v242, v242
	v_pk_mul_f32 v[240:241], v[240:241], v[164:165]
	v_cos_f32_e32 v243, v243
	v_pk_mul_f32 v[208:209], v[16:17], v[170:171] op_sel_hi:[1,0]
	v_pk_mul_f32 v[242:243], v[242:243], v[164:165]
	v_pk_mul_f32 v[208:209], v[208:209], v[132:133]
	v_pk_mul_f32 v[214:215], v[10:11], v[170:171] op_sel_hi:[1,0]
	v_pk_mul_f32 v[214:215], v[214:215], v[138:139]
	v_pk_mul_f32 v[216:217], v[12:13], v[170:171] op_sel_hi:[1,0]
	v_pk_mul_f32 v[216:217], v[216:217], v[140:141]
	v_pk_mul_f32 v[210:211], v[6:7], v[170:171] op_sel_hi:[1,0]
	v_pk_mul_f32 v[210:211], v[210:211], v[134:135]
	v_pk_mul_f32 v[212:213], v[8:9], v[170:171] op_sel_hi:[1,0]
	v_pk_mul_f32 v[212:213], v[212:213], v[136:137]
	v_pk_mul_f32 v[218:219], v[2:3], v[170:171] op_sel_hi:[1,0]
	v_pk_mul_f32 v[218:219], v[218:219], v[142:143]
	v_pk_mul_f32 v[220:221], v[4:5], v[170:171] op_sel_hi:[1,0]
	v_pk_mul_f32 v[220:221], v[220:221], v[144:145]
	v_pk_mul_f32 v[230:231], v[214:215], v[244:245]
	v_pk_fma_f32 v[222:223], v[206:207], v[236:237], v[230:231] neg_lo:[0,0,1] neg_hi:[0,0,1]
	v_pk_mul_f32 v[230:231], v[206:207], v[244:245]
	v_pk_fma_f32 v[214:215], v[214:215], v[236:237], v[230:231]
	v_pk_mul_f32 v[174:175], v[216:217], v[246:247]
	v_pk_fma_f32 v[224:225], v[208:209], v[238:239], v[174:175] neg_lo:[0,0,1] neg_hi:[0,0,1]
	v_pk_mul_f32 v[174:175], v[208:209], v[246:247]
	v_pk_fma_f32 v[216:217], v[216:217], v[238:239], v[174:175]
	v_pk_mul_f32 v[230:231], v[218:219], v[248:249]
	v_pk_fma_f32 v[226:227], v[210:211], v[240:241], v[230:231] neg_lo:[0,0,1] neg_hi:[0,0,1]
	v_pk_mul_f32 v[230:231], v[210:211], v[248:249]
	v_pk_fma_f32 v[218:219], v[218:219], v[240:241], v[230:231]
	v_pk_mul_f32 v[174:175], v[220:221], v[250:251]
	v_pk_fma_f32 v[228:229], v[212:213], v[242:243], v[174:175] neg_lo:[0,0,1] neg_hi:[0,0,1]
	v_pk_mul_f32 v[174:175], v[212:213], v[250:251]
	v_pk_fma_f32 v[220:221], v[220:221], v[242:243], v[174:175]
	v_cvt_pk_bf16_f32 v222, v222, v223
	v_cvt_pk_bf16_f32 v223, v224, v225
	v_cvt_pk_bf16_f32 v224, v226, v227
	v_cvt_pk_bf16_f32 v225, v228, v229
	v_cvt_pk_bf16_f32 v214, v214, v215
	v_cvt_pk_bf16_f32 v215, v216, v217
	v_cvt_pk_bf16_f32 v216, v218, v219
	v_cvt_pk_bf16_f32 v217, v220, v221
	v_permlane16_swap_b32_e32 v222, v224
	v_permlane16_swap_b32_e32 v223, v225
	v_permlane16_swap_b32_e32 v214, v216
	v_permlane16_swap_b32_e32 v215, v217
	global_store_dwordx4 v[172:173], v[222:225], off
	global_store_dwordx4 v[172:173], v[214:217], off offset:64
	s_branch .LBB0_816
